# GEMM K-loops: loop counter / pointer increments / exit compare rotated ahead of the loop-back barrier (6 loops)
# baseline (speedup 1.0000x reference)
; #define PG8_STAGE(bufoff, gbase, voff) do { _Pragma("unroll") for (int _i = 0; _i < 2; ++_i) \
;         __builtin_amdgcn_global_load_lds((const unsigned*)((const char*)(gbase) + (voff)[_i]), (PG8_LAS unsigned*)(lds + (bufoff) + ldsw + _i * 8192), 16, 0, 0); } while (0)
; #define PG8_LDA(dst, b, h) do { _Pragma("unroll") for (int m = 0; m < 4; ++m) _Pragma("unroll") for (int k = 0; k < 2; ++k) dst[m][k] = *(const PG8_LAS bf16x8*)(lds + PG8_SA(b, h) + aoff + m * 2048 + k * 1024); } while (0)
; #define PG8_LDB(dst, b, h) do { _Pragma("unroll") for (int n = 0; n < 2; ++n) _Pragma("unroll") for (int k = 0; k < 2; ++k) dst[n][k] = *(const PG8_LAS bf16x8*)(lds + PG8_SB(b, h) + boff + n * 2048 + k * 1024); } while (0)
; #define PG8_MMA(ai, bj, At, Bt) do { __builtin_amdgcn_s_setprio(1); _Pragma("unroll") for (int m = 0; m < 4; ++m) _Pragma("unroll") for (int n = 0; n < 2; ++n) _Pragma("unroll") for (int k = 0; k < 2; ++k) \
;         acc[ai][bj][m][n] = mma16<Epi::F16>(Bt[n][k], At[m][k], acc[ai][bj][m][n]); __builtin_amdgcn_s_setprio(0); } while (0)
; #define PG8_WAIT_V(n) asm volatile("s_waitcnt vmcnt(" #n ")" ::: "memory")
; #define PG8_WAIT_L(n) asm volatile("s_waitcnt lgkmcnt(" #n ")" ::: "memory")
; #define PG8_BAR __builtin_amdgcn_s_barrier()
; #define PG8_SCHED __builtin_amdgcn_sched_barrier(0)
; template <class Epi, class Sched, bool ALIGN_EPI = false, bool SP2 = false>
; __device__ __forceinline__ void gemm_phase(PG8_LAS unsigned char* lds, const Gemm g, const Sched& S, const Epi& E, const int wave_in) {
;     ...
;             PG8_LDB(B0, 0, 0); PG8_LDB(B1, 0, 1); PG8_SCHED; PG8_LDA(At, 0, 0); PG8_STAGE(PG8_SA(1, 1), a1 + hstep, voffA);
;             PG8_WAIT_V(8); PG8_WAIT_L(0); PG8_BAR; PG8_MMA(0, 0, At, B0); PG8_MMA(0, 1, At, B1); PG8_BAR; PG8_SCHED;
;             PG8_LDA(At, 0, 1); PG8_STAGE(PG8_SB(0, 0), b2, voffB); PG8_STAGE(PG8_SB(0, 1), b2 + hstep, voffB); PG8_STAGE(PG8_SA(0, 0), a2, voffA);
;             PG8_WAIT_V(8); PG8_WAIT_L(0); PG8_BAR; PG8_MMA(1, 0, At, B0); PG8_MMA(1, 1, At, B1); PG8_BAR; PG8_SCHED;
.LBB0_320:
	s_add_u32 s14, s38, 0xfffc0080
	s_addc_u32 s15, s39, -1
	s_cmp_eq_u32 s76, 12
	s_cselect_b32 s91, s10, s15
	s_cselect_b32 s90, s11, s14
	s_cselect_b32 s37, s59, s13
	s_cselect_b32 s36, s61, s12
	s_add_i32 s72, 0, 0x14000
	v_add_u32_e32 v154, s72, v179
	ds_read_b128 v[114:117], v185
	ds_read_b128 v[118:121], v185 offset:1024
	ds_read_b128 v[122:125], v185 offset:2048
	ds_read_b128 v[130:133], v185 offset:3072
	ds_read_b128 v[138:141], v154
	ds_read_b128 v[142:145], v154 offset:1024
	ds_read_b128 v[146:149], v154 offset:2048
	ds_read_b128 v[154:157], v154 offset:3072
	v_lshl_add_u64 v[216:217], s[38:39], 0, v[168:169]
	s_add_i32 m0, s1, 0xc000
	ds_read_b128 v[172:175], v183
	ds_read_b128 v[186:189], v183 offset:1024
	ds_read_b128 v[190:193], v183 offset:2048
	ds_read_b128 v[194:197], v183 offset:3072
	ds_read_b128 v[198:201], v183 offset:4096
	ds_read_b128 v[202:205], v183 offset:5120
	ds_read_b128 v[208:211], v183 offset:6144
	ds_read_b128 v[212:215], v183 offset:7168
	global_load_lds_dwordx4 v[216:217], off
	v_lshl_add_u64 v[216:217], s[38:39], 0, v[170:171]
	s_add_i32 m0, s1, 0xe000
	s_nop 0
	global_load_lds_dwordx4 v[216:217], off
	s_waitcnt vmcnt(8)
	s_waitcnt lgkmcnt(0)
	s_barrier
	s_setprio 1
	s_waitcnt lgkmcnt(0)
	v_mfma_f32_16x16x32_f16 v[158:161], v[114:117], v[172:175], v[158:161]
	v_mfma_f32_16x16x32_f16 v[150:153], v[122:125], v[172:175], v[150:153]
	v_mfma_f32_16x16x32_f16 v[110:113], v[114:117], v[190:193], v[110:113]
	v_mfma_f32_16x16x32_f16 v[106:109], v[122:125], v[190:193], v[106:109]
	v_mfma_f32_16x16x32_f16 v[94:97], v[114:117], v[198:201], v[94:97]
	v_mfma_f32_16x16x32_f16 v[90:93], v[122:125], v[198:201], v[90:93]
	v_mfma_f32_16x16x32_f16 v[78:81], v[114:117], v[208:211], v[78:81]
	v_mfma_f32_16x16x32_f16 v[74:77], v[122:125], v[208:211], v[74:77]
	v_mfma_f32_16x16x32_f16 v[158:161], v[118:121], v[186:189], v[158:161]
	v_mfma_f32_16x16x32_f16 v[150:153], v[130:133], v[186:189], v[150:153]
	v_mfma_f32_16x16x32_f16 v[110:113], v[118:121], v[194:197], v[110:113]
	v_mfma_f32_16x16x32_f16 v[106:109], v[130:133], v[194:197], v[106:109]
	v_mfma_f32_16x16x32_f16 v[94:97], v[118:121], v[202:205], v[94:97]
	v_mfma_f32_16x16x32_f16 v[90:93], v[130:133], v[202:205], v[90:93]
	v_mfma_f32_16x16x32_f16 v[78:81], v[118:121], v[212:215], v[78:81]
	v_mfma_f32_16x16x32_f16 v[74:77], v[130:133], v[212:215], v[74:77]
	s_setprio 0
	s_setprio 1
	v_mfma_f32_16x16x32_f16 v[134:137], v[138:141], v[172:175], v[134:137]
	v_mfma_f32_16x16x32_f16 v[126:129], v[146:149], v[172:175], v[126:129]
	v_mfma_f32_16x16x32_f16 v[102:105], v[138:141], v[190:193], v[102:105]
	v_mfma_f32_16x16x32_f16 v[98:101], v[146:149], v[190:193], v[98:101]
	v_mfma_f32_16x16x32_f16 v[86:89], v[138:141], v[198:201], v[86:89]
	v_mfma_f32_16x16x32_f16 v[82:85], v[146:149], v[198:201], v[82:85]
	v_mfma_f32_16x16x32_f16 v[70:73], v[138:141], v[208:211], v[70:73]
	v_mfma_f32_16x16x32_f16 v[66:69], v[146:149], v[208:211], v[66:69]
	v_mfma_f32_16x16x32_f16 v[134:137], v[142:145], v[186:189], v[134:137]
	v_mfma_f32_16x16x32_f16 v[126:129], v[154:157], v[186:189], v[126:129]
	v_mfma_f32_16x16x32_f16 v[102:105], v[142:145], v[194:197], v[102:105]
	v_mfma_f32_16x16x32_f16 v[98:101], v[154:157], v[194:197], v[98:101]
	v_mfma_f32_16x16x32_f16 v[86:89], v[142:145], v[202:205], v[86:89]
	v_mfma_f32_16x16x32_f16 v[82:85], v[154:157], v[202:205], v[82:85]
	v_mfma_f32_16x16x32_f16 v[70:73], v[142:145], v[212:215], v[70:73]
	v_mfma_f32_16x16x32_f16 v[66:69], v[154:157], v[212:215], v[66:69]
	s_setprio 0
	s_barrier
	s_add_i32 s14, s28, s0
	v_lshl_add_u64 v[216:217], s[36:37], 0, v[0:1]
	s_mov_b32 m0, s14
	ds_read_b128 v[172:175], v183 offset:16384
	ds_read_b128 v[186:189], v183 offset:17408
	ds_read_b128 v[190:193], v183 offset:18432
	ds_read_b128 v[194:197], v183 offset:19456
	ds_read_b128 v[198:201], v183 offset:20480
	ds_read_b128 v[202:205], v183 offset:21504
	ds_read_b128 v[208:211], v183 offset:22528
	ds_read_b128 v[212:215], v183 offset:23552
	global_load_lds_dwordx4 v[216:217], off
	s_add_i32 m0, s14, 0x2000
	s_add_u32 s82, s36, 0x40000
	v_lshl_add_u64 v[218:219], s[36:37], 0, v[166:167]
	s_addc_u32 s83, s37, 0
	s_add_i32 s14, s72, s0
	global_load_lds_dwordx4 v[218:219], off
	v_lshl_add_u64 v[220:221], s[82:83], 0, v[0:1]
	s_mov_b32 m0, s14
	v_lshl_add_u64 v[222:223], s[90:91], 0, v[164:165]
	global_load_lds_dwordx4 v[220:221], off
	v_lshl_add_u64 v[220:221], s[82:83], 0, v[166:167]
	s_add_i32 m0, s14, 0x2000
	s_nop 0
	global_load_lds_dwordx4 v[220:221], off
	v_lshl_add_u64 v[220:221], s[90:91], 0, v[162:163]
	s_mov_b32 m0, s1
	s_nop 0
	global_load_lds_dwordx4 v[220:221], off
	s_mov_b32 m0, s4
	s_nop 0
	global_load_lds_dwordx4 v[222:223], off
	s_waitcnt vmcnt(8)
	s_waitcnt lgkmcnt(0)
	s_barrier
; #define PG8_STAGE(bufoff, gbase, voff) do { _Pragma("unroll") for (int _i = 0; _i < 2; ++_i) \
;         __builtin_amdgcn_global_load_lds((const unsigned*)((const char*)(gbase) + (voff)[_i]), (PG8_LAS unsigned*)(lds + (bufoff) + ldsw + _i * 8192), 16, 0, 0); } while (0)
; #define PG8_LDA(dst, b, h) do { _Pragma("unroll") for (int m = 0; m < 4; ++m) _Pragma("unroll") for (int k = 0; k < 2; ++k) dst[m][k] = *(const PG8_LAS bf16x8*)(lds + PG8_SA(b, h) + aoff + m * 2048 + k * 1024); } while (0)
; #define PG8_LDB(dst, b, h) do { _Pragma("unroll") for (int n = 0; n < 2; ++n) _Pragma("unroll") for (int k = 0; k < 2; ++k) dst[n][k] = *(const PG8_LAS bf16x8*)(lds + PG8_SB(b, h) + boff + n * 2048 + k * 1024); } while (0)
; #define PG8_MMA(ai, bj, At, Bt) do { __builtin_amdgcn_s_setprio(1); _Pragma("unroll") for (int m = 0; m < 4; ++m) _Pragma("unroll") for (int n = 0; n < 2; ++n) _Pragma("unroll") for (int k = 0; k < 2; ++k) \
;         acc[ai][bj][m][n] = mma16<Epi::F16>(Bt[n][k], At[m][k], acc[ai][bj][m][n]); __builtin_amdgcn_s_setprio(0); } while (0)
; #define PG8_WAIT_V(n) asm volatile("s_waitcnt vmcnt(" #n ")" ::: "memory")
; #define PG8_WAIT_L(n) asm volatile("s_waitcnt lgkmcnt(" #n ")" ::: "memory")
; #define PG8_BAR __builtin_amdgcn_s_barrier()
; #define PG8_SCHED __builtin_amdgcn_sched_barrier(0)
; template <class Epi, class Sched, bool ALIGN_EPI = false, bool SP2 = false>
; __device__ __forceinline__ void gemm_phase(PG8_LAS unsigned char* lds, const Gemm g, const Sched& S, const Epi& E, const int wave_in) {
;     ...
;             PG8_WAIT_V(8); PG8_WAIT_L(0); PG8_BAR; PG8_MMA(1, 0, At, B0); PG8_MMA(1, 1, At, B1); PG8_BAR; PG8_SCHED;
;             PG8_LDB(B0, 1, 0); PG8_LDB(B1, 1, 1); PG8_SCHED; PG8_LDA(At, 1, 0); PG8_STAGE(PG8_SA(0, 1), a2 + hstep, voffA);
;             PG8_WAIT_V(8); PG8_WAIT_L(0); PG8_BAR; PG8_MMA(0, 0, At, B0); PG8_MMA(0, 1, At, B1); PG8_BAR; PG8_SCHED;
	s_setprio 1
	s_waitcnt lgkmcnt(0)
	v_mfma_f32_16x16x32_f16 v[62:65], v[114:117], v[172:175], v[62:65]
	v_mfma_f32_16x16x32_f16 v[58:61], v[122:125], v[172:175], v[58:61]
	v_mfma_f32_16x16x32_f16 v[46:49], v[114:117], v[190:193], v[46:49]
	v_mfma_f32_16x16x32_f16 v[42:45], v[122:125], v[190:193], v[42:45]
	v_mfma_f32_16x16x32_f16 v[30:33], v[114:117], v[198:201], v[30:33]
	v_mfma_f32_16x16x32_f16 v[26:29], v[122:125], v[198:201], v[26:29]
	v_mfma_f32_16x16x32_f16 v[14:17], v[114:117], v[208:211], v[14:17]
	v_mfma_f32_16x16x32_f16 v[10:13], v[122:125], v[208:211], v[10:13]
	v_mfma_f32_16x16x32_f16 v[62:65], v[118:121], v[186:189], v[62:65]
	v_mfma_f32_16x16x32_f16 v[58:61], v[130:133], v[186:189], v[58:61]
	v_mfma_f32_16x16x32_f16 v[46:49], v[118:121], v[194:197], v[46:49]
	v_mfma_f32_16x16x32_f16 v[42:45], v[130:133], v[194:197], v[42:45]
	v_mfma_f32_16x16x32_f16 v[30:33], v[118:121], v[202:205], v[30:33]
	v_mfma_f32_16x16x32_f16 v[26:29], v[130:133], v[202:205], v[26:29]
	v_mfma_f32_16x16x32_f16 v[14:17], v[118:121], v[212:215], v[14:17]
	v_mfma_f32_16x16x32_f16 v[10:13], v[130:133], v[212:215], v[10:13]
	s_setprio 0
	s_setprio 1
	v_mfma_f32_16x16x32_f16 v[54:57], v[138:141], v[172:175], v[54:57]
	v_mfma_f32_16x16x32_f16 v[50:53], v[146:149], v[172:175], v[50:53]
	v_mfma_f32_16x16x32_f16 v[38:41], v[138:141], v[190:193], v[38:41]
	v_mfma_f32_16x16x32_f16 v[34:37], v[146:149], v[190:193], v[34:37]
	v_mfma_f32_16x16x32_f16 v[22:25], v[138:141], v[198:201], v[22:25]
	v_mfma_f32_16x16x32_f16 v[18:21], v[146:149], v[198:201], v[18:21]
	v_mfma_f32_16x16x32_f16 v[6:9], v[138:141], v[208:211], v[6:9]
	v_mfma_f32_16x16x32_f16 v[2:5], v[146:149], v[208:211], v[2:5]
	v_mfma_f32_16x16x32_f16 v[54:57], v[142:145], v[186:189], v[54:57]
	v_mfma_f32_16x16x32_f16 v[50:53], v[154:157], v[186:189], v[50:53]
	v_mfma_f32_16x16x32_f16 v[38:41], v[142:145], v[194:197], v[38:41]
	v_mfma_f32_16x16x32_f16 v[34:37], v[154:157], v[194:197], v[34:37]
	v_mfma_f32_16x16x32_f16 v[22:25], v[142:145], v[202:205], v[22:25]
	v_mfma_f32_16x16x32_f16 v[18:21], v[154:157], v[202:205], v[18:21]
	v_mfma_f32_16x16x32_f16 v[6:9], v[142:145], v[212:215], v[6:9]
	v_mfma_f32_16x16x32_f16 v[2:5], v[154:157], v[212:215], v[2:5]
	s_setprio 0
	s_barrier
	s_add_i32 s73, 0, 0x18000
	s_add_i32 s74, 0, 0x1c000
	v_add_u32_e32 v130, s73, v179
	v_add_u32_e32 v154, s74, v179
	ds_read_b128 v[114:117], v130
	ds_read_b128 v[118:121], v130 offset:1024
	ds_read_b128 v[122:125], v130 offset:2048
	ds_read_b128 v[130:133], v130 offset:3072
	ds_read_b128 v[138:141], v154
	ds_read_b128 v[142:145], v154 offset:1024
	ds_read_b128 v[146:149], v154 offset:2048
	ds_read_b128 v[154:157], v154 offset:3072
	s_add_u32 s82, s90, 0x40000
	s_addc_u32 s83, s91, 0
	s_mov_b32 m0, s5
	v_lshl_add_u64 v[224:225], s[82:83], 0, v[162:163]
	ds_read_b128 v[172:175], v183 offset:32768
	ds_read_b128 v[186:189], v183 offset:33792
	ds_read_b128 v[190:193], v183 offset:34816
	ds_read_b128 v[194:197], v183 offset:35840
	ds_read_b128 v[198:201], v183 offset:36864
	ds_read_b128 v[202:205], v183 offset:37888
	ds_read_b128 v[208:211], v183 offset:38912
	ds_read_b128 v[212:215], v183 offset:39936
	global_load_lds_dwordx4 v[224:225], off
	v_lshl_add_u64 v[224:225], s[82:83], 0, v[164:165]
	s_mov_b32 m0, s6
	s_nop 0
	global_load_lds_dwordx4 v[224:225], off
	s_waitcnt vmcnt(8)
	s_waitcnt lgkmcnt(0)
	s_barrier
	s_setprio 1
	s_waitcnt lgkmcnt(0)
	v_mfma_f32_16x16x32_f16 v[158:161], v[114:117], v[172:175], v[158:161]
	v_mfma_f32_16x16x32_f16 v[150:153], v[122:125], v[172:175], v[150:153]
	v_mfma_f32_16x16x32_f16 v[110:113], v[114:117], v[190:193], v[110:113]
	v_mfma_f32_16x16x32_f16 v[106:109], v[122:125], v[190:193], v[106:109]
	v_mfma_f32_16x16x32_f16 v[94:97], v[114:117], v[198:201], v[94:97]
	v_mfma_f32_16x16x32_f16 v[90:93], v[122:125], v[198:201], v[90:93]
	v_mfma_f32_16x16x32_f16 v[78:81], v[114:117], v[208:211], v[78:81]
	v_mfma_f32_16x16x32_f16 v[74:77], v[122:125], v[208:211], v[74:77]
	v_mfma_f32_16x16x32_f16 v[158:161], v[118:121], v[186:189], v[158:161]
	v_mfma_f32_16x16x32_f16 v[150:153], v[130:133], v[186:189], v[150:153]
	v_mfma_f32_16x16x32_f16 v[110:113], v[118:121], v[194:197], v[110:113]
	v_mfma_f32_16x16x32_f16 v[106:109], v[130:133], v[194:197], v[106:109]
	v_mfma_f32_16x16x32_f16 v[94:97], v[118:121], v[202:205], v[94:97]
	v_mfma_f32_16x16x32_f16 v[90:93], v[130:133], v[202:205], v[90:93]
	v_mfma_f32_16x16x32_f16 v[78:81], v[118:121], v[212:215], v[78:81]
	v_mfma_f32_16x16x32_f16 v[74:77], v[130:133], v[212:215], v[74:77]
	s_setprio 0
	s_setprio 1
	v_mfma_f32_16x16x32_f16 v[134:137], v[138:141], v[172:175], v[134:137]
	v_mfma_f32_16x16x32_f16 v[126:129], v[146:149], v[172:175], v[126:129]
	v_mfma_f32_16x16x32_f16 v[102:105], v[138:141], v[190:193], v[102:105]
	v_mfma_f32_16x16x32_f16 v[98:101], v[146:149], v[190:193], v[98:101]
	v_mfma_f32_16x16x32_f16 v[86:89], v[138:141], v[198:201], v[86:89]
	v_mfma_f32_16x16x32_f16 v[82:85], v[146:149], v[198:201], v[82:85]
	v_mfma_f32_16x16x32_f16 v[70:73], v[138:141], v[208:211], v[70:73]
	v_mfma_f32_16x16x32_f16 v[66:69], v[146:149], v[208:211], v[66:69]
	v_mfma_f32_16x16x32_f16 v[134:137], v[142:145], v[186:189], v[134:137]
	v_mfma_f32_16x16x32_f16 v[126:129], v[154:157], v[186:189], v[126:129]
	v_mfma_f32_16x16x32_f16 v[102:105], v[142:145], v[194:197], v[102:105]
	v_mfma_f32_16x16x32_f16 v[98:101], v[154:157], v[194:197], v[98:101]
	v_mfma_f32_16x16x32_f16 v[86:89], v[142:145], v[202:205], v[86:89]
	v_mfma_f32_16x16x32_f16 v[82:85], v[154:157], v[202:205], v[82:85]
	v_mfma_f32_16x16x32_f16 v[70:73], v[142:145], v[212:215], v[70:73]
	v_mfma_f32_16x16x32_f16 v[66:69], v[154:157], v[212:215], v[66:69]
	s_setprio 0
	s_barrier
; #define PG8_STAGE(bufoff, gbase, voff) do { _Pragma("unroll") for (int _i = 0; _i < 2; ++_i) \
;         __builtin_amdgcn_global_load_lds((const unsigned*)((const char*)(gbase) + (voff)[_i]), (PG8_LAS unsigned*)(lds + (bufoff) + ldsw + _i * 8192), 16, 0, 0); } while (0)
; #define PG8_LDA(dst, b, h) do { _Pragma("unroll") for (int m = 0; m < 4; ++m) _Pragma("unroll") for (int k = 0; k < 2; ++k) dst[m][k] = *(const PG8_LAS bf16x8*)(lds + PG8_SA(b, h) + aoff + m * 2048 + k * 1024); } while (0)
; #define PG8_MMA(ai, bj, At, Bt) do { __builtin_amdgcn_s_setprio(1); _Pragma("unroll") for (int m = 0; m < 4; ++m) _Pragma("unroll") for (int n = 0; n < 2; ++n) _Pragma("unroll") for (int k = 0; k < 2; ++k) \
;         acc[ai][bj][m][n] = mma16<Epi::F16>(Bt[n][k], At[m][k], acc[ai][bj][m][n]); __builtin_amdgcn_s_setprio(0); } while (0)
; #define PG8_WAIT_V(n) asm volatile("s_waitcnt vmcnt(" #n ")" ::: "memory")
; #define PG8_WAIT_L(n) asm volatile("s_waitcnt lgkmcnt(" #n ")" ::: "memory")
; #define PG8_BAR __builtin_amdgcn_s_barrier()
; #define PG8_SCHED __builtin_amdgcn_sched_barrier(0)
; template <class Epi, class Sched, bool ALIGN_EPI = false, bool SP2 = false>
; __device__ __forceinline__ void gemm_phase(PG8_LAS unsigned char* lds, const Gemm g, const Sched& S, const Epi& E, const int wave_in) {
;     ...
;         for (int t = 0; t < nt; t += 2) {
;     ...
;             PG8_LDA(At, 1, 1); PG8_STAGE(PG8_SB(1, 0), b3, voffB); PG8_STAGE(PG8_SB(1, 1), b3 + hstep, voffB); PG8_STAGE(PG8_SA(1, 0), a3, voffA);
;             PG8_WAIT_V(8); PG8_WAIT_L(0); PG8_BAR; PG8_MMA(1, 0, At, B0); PG8_MMA(1, 1, At, B1); PG8_BAR; PG8_SCHED;
	s_add_i32 s14, s73, s0
	v_lshl_add_u64 v[216:217], v[216:217], 0, s[78:79]
	s_mov_b32 m0, s14
	ds_read_b128 v[172:175], v183 offset:49152
	ds_read_b128 v[186:189], v183 offset:50176
	ds_read_b128 v[190:193], v183 offset:51200
	ds_read_b128 v[194:197], v183 offset:52224
	ds_read_b128 v[198:201], v183 offset:53248
	ds_read_b128 v[202:205], v183 offset:54272
	ds_read_b128 v[208:211], v183 offset:55296
	ds_read_b128 v[212:215], v183 offset:56320
	global_load_lds_dwordx4 v[216:217], off
	s_add_i32 m0, s14, 0x2000
	s_add_u32 s36, s36, 0x40080
	v_lshl_add_u64 v[216:217], v[218:219], 0, s[78:79]
	s_addc_u32 s37, s37, 0
	s_add_i32 s14, s74, s0
	global_load_lds_dwordx4 v[216:217], off
	v_lshl_add_u64 v[216:217], s[36:37], 0, v[0:1]
	s_mov_b32 m0, s14
	s_nop 0
	global_load_lds_dwordx4 v[216:217], off
	v_lshl_add_u64 v[216:217], s[36:37], 0, v[166:167]
	s_add_i32 m0, s14, 0x2000
	s_nop 0
	global_load_lds_dwordx4 v[216:217], off
	v_lshl_add_u64 v[216:217], v[220:221], 0, s[78:79]
	s_mov_b32 m0, s7
	s_nop 0
	global_load_lds_dwordx4 v[216:217], off
	v_lshl_add_u64 v[216:217], v[222:223], 0, s[78:79]
	s_mov_b32 m0, s8
	s_nop 0
	global_load_lds_dwordx4 v[216:217], off
	s_waitcnt vmcnt(8)
	s_waitcnt lgkmcnt(0)
	s_barrier
	s_setprio 1
	s_waitcnt lgkmcnt(0)
	v_mfma_f32_16x16x32_f16 v[62:65], v[114:117], v[172:175], v[62:65]
	v_mfma_f32_16x16x32_f16 v[58:61], v[122:125], v[172:175], v[58:61]
	v_mfma_f32_16x16x32_f16 v[46:49], v[114:117], v[190:193], v[46:49]
	v_mfma_f32_16x16x32_f16 v[42:45], v[122:125], v[190:193], v[42:45]
	v_mfma_f32_16x16x32_f16 v[30:33], v[114:117], v[198:201], v[30:33]
	v_mfma_f32_16x16x32_f16 v[26:29], v[122:125], v[198:201], v[26:29]
	v_mfma_f32_16x16x32_f16 v[14:17], v[114:117], v[208:211], v[14:17]
	v_mfma_f32_16x16x32_f16 v[10:13], v[122:125], v[208:211], v[10:13]
	v_mfma_f32_16x16x32_f16 v[62:65], v[118:121], v[186:189], v[62:65]
	v_mfma_f32_16x16x32_f16 v[58:61], v[130:133], v[186:189], v[58:61]
	v_mfma_f32_16x16x32_f16 v[46:49], v[118:121], v[194:197], v[46:49]
	v_mfma_f32_16x16x32_f16 v[42:45], v[130:133], v[194:197], v[42:45]
	v_mfma_f32_16x16x32_f16 v[30:33], v[118:121], v[202:205], v[30:33]
	v_mfma_f32_16x16x32_f16 v[26:29], v[130:133], v[202:205], v[26:29]
	v_mfma_f32_16x16x32_f16 v[14:17], v[118:121], v[212:215], v[14:17]
	v_mfma_f32_16x16x32_f16 v[10:13], v[130:133], v[212:215], v[10:13]
	s_setprio 0
	s_setprio 1
	v_mfma_f32_16x16x32_f16 v[54:57], v[138:141], v[172:175], v[54:57]
	v_mfma_f32_16x16x32_f16 v[50:53], v[146:149], v[172:175], v[50:53]
	v_mfma_f32_16x16x32_f16 v[38:41], v[138:141], v[190:193], v[38:41]
	v_mfma_f32_16x16x32_f16 v[34:37], v[146:149], v[190:193], v[34:37]
	v_mfma_f32_16x16x32_f16 v[22:25], v[138:141], v[198:201], v[22:25]
	v_mfma_f32_16x16x32_f16 v[18:21], v[146:149], v[198:201], v[18:21]
	v_mfma_f32_16x16x32_f16 v[6:9], v[138:141], v[208:211], v[6:9]
	v_mfma_f32_16x16x32_f16 v[2:5], v[146:149], v[208:211], v[2:5]
	v_mfma_f32_16x16x32_f16 v[54:57], v[142:145], v[186:189], v[54:57]
	v_mfma_f32_16x16x32_f16 v[50:53], v[154:157], v[186:189], v[50:53]
	v_mfma_f32_16x16x32_f16 v[38:41], v[142:145], v[194:197], v[38:41]
	v_mfma_f32_16x16x32_f16 v[34:37], v[154:157], v[194:197], v[34:37]
	v_mfma_f32_16x16x32_f16 v[22:25], v[142:145], v[202:205], v[22:25]
	v_mfma_f32_16x16x32_f16 v[18:21], v[154:157], v[202:205], v[18:21]
	v_mfma_f32_16x16x32_f16 v[6:9], v[142:145], v[212:215], v[6:9]
	v_mfma_f32_16x16x32_f16 v[2:5], v[154:157], v[212:215], v[2:5]
	s_setprio 0
	s_add_i32 s76, s76, 2
	s_add_u32 s38, s38, 0x100
	s_addc_u32 s39, s39, 0
	s_add_u32 s12, s12, 0x100
	s_addc_u32 s13, s13, 0
	s_cmp_gt_u32 s76, 13
	s_barrier
	s_cbranch_scc0 .LBB0_320
	s_and_b64 vcc, exec, s[54:55]
	s_cbranch_vccz .LBB0_323
	s_barrier

; #define PG8_STAGE(bufoff, gbase, voff) do { _Pragma("unroll") for (int _i = 0; _i < 2; ++_i) \
;         __builtin_amdgcn_global_load_lds((const unsigned*)((const char*)(gbase) + (voff)[_i]), (PG8_LAS unsigned*)(lds + (bufoff) + ldsw + _i * 8192), 16, 0, 0); } while (0)
; #define PG8_LDA(dst, b, h) do { _Pragma("unroll") for (int m = 0; m < 4; ++m) _Pragma("unroll") for (int k = 0; k < 2; ++k) dst[m][k] = *(const PG8_LAS bf16x8*)(lds + PG8_SA(b, h) + aoff + m * 2048 + k * 1024); } while (0)
; #define PG8_LDB(dst, b, h) do { _Pragma("unroll") for (int n = 0; n < 2; ++n) _Pragma("unroll") for (int k = 0; k < 2; ++k) dst[n][k] = *(const PG8_LAS bf16x8*)(lds + PG8_SB(b, h) + boff + n * 2048 + k * 1024); } while (0)
; #define PG8_MMA(ai, bj, At, Bt) do { __builtin_amdgcn_s_setprio(1); _Pragma("unroll") for (int m = 0; m < 4; ++m) _Pragma("unroll") for (int n = 0; n < 2; ++n) _Pragma("unroll") for (int k = 0; k < 2; ++k) \
;         acc[ai][bj][m][n] = mma16<Epi::F16>(Bt[n][k], At[m][k], acc[ai][bj][m][n]); __builtin_amdgcn_s_setprio(0); } while (0)
; #define PG8_WAIT_V(n) asm volatile("s_waitcnt vmcnt(" #n ")" ::: "memory")
; #define PG8_WAIT_L(n) asm volatile("s_waitcnt lgkmcnt(" #n ")" ::: "memory")
; #define PG8_BAR __builtin_amdgcn_s_barrier()
; #define PG8_SCHED __builtin_amdgcn_sched_barrier(0)
; template <class Epi, class Sched, bool ALIGN_EPI = false, bool SP2 = false>
; __device__ __forceinline__ void gemm_phase(PG8_LAS unsigned char* lds, const Gemm g, const Sched& S, const Epi& E, const int wave_in) {
;     ...
;             PG8_LDB(B0, 0, 0); PG8_LDB(B1, 0, 1); PG8_SCHED; PG8_LDA(At, 0, 0); PG8_STAGE(PG8_SA(1, 1), a1 + hstep, voffA);
;             PG8_WAIT_V(8); PG8_WAIT_L(0); PG8_BAR; PG8_MMA(0, 0, At, B0); PG8_MMA(0, 1, At, B1); PG8_BAR; PG8_SCHED;
;             PG8_LDA(At, 0, 1); PG8_STAGE(PG8_SB(0, 0), b2, voffB); PG8_STAGE(PG8_SB(0, 1), b2 + hstep, voffB); PG8_STAGE(PG8_SA(0, 0), a2, voffA);
;             PG8_WAIT_V(8); PG8_WAIT_L(0); PG8_BAR; PG8_MMA(1, 0, At, B0); PG8_MMA(1, 1, At, B1); PG8_BAR; PG8_SCHED;
.LBB0_418:
	v_add_u32_e32 v58, s28, v211
	v_add_u32_e32 v78, s72, v211
	ds_read_b128 v[42:45], v58
	ds_read_b128 v[46:49], v58 offset:1024
	ds_read_b128 v[54:57], v58 offset:2048
	ds_read_b128 v[58:61], v58 offset:3072
	ds_read_b128 v[66:69], v78
	ds_read_b128 v[70:73], v78 offset:1024
	ds_read_b128 v[74:77], v78 offset:2048
	ds_read_b128 v[78:81], v78 offset:3072
	s_add_u32 s86, s62, 0x100
	s_addc_u32 s87, s63, 0
	s_cmp_eq_u32 s13, 40
	s_cselect_b32 s91, s45, s87
	s_cselect_b32 s90, s44, s86
	s_cselect_b32 s37, s61, s12
	s_cselect_b32 s36, s60, s11
	v_lshl_add_u64 v[178:179], s[62:63], 0, v[220:221]
	s_add_i32 m0, s0, 0xc000
	ds_read_b128 v[98:101], v213
	ds_read_b128 v[102:105], v213 offset:1024
	ds_read_b128 v[106:109], v213 offset:2048
	ds_read_b128 v[118:121], v213 offset:3072
	ds_read_b128 v[130:133], v213 offset:4096
	ds_read_b128 v[138:141], v213 offset:5120
	ds_read_b128 v[146:149], v213 offset:6144
	ds_read_b128 v[158:161], v213 offset:7168
	global_load_lds_dwordx4 v[178:179], off
	v_lshl_add_u64 v[178:179], s[62:63], 0, v[222:223]
	s_add_i32 m0, s0, 0xe000
	s_nop 0
	global_load_lds_dwordx4 v[178:179], off
	s_waitcnt vmcnt(8)
	s_waitcnt lgkmcnt(0)
	s_barrier
	s_setprio 1
	s_waitcnt lgkmcnt(0)
	v_mfma_f32_16x16x32_bf16 v[190:193], v[54:57], v[98:101], v[190:193]
	v_mfma_f32_16x16x32_bf16 v[174:177], v[42:45], v[106:109], v[174:177]
	v_mfma_f32_16x16x32_bf16 v[170:173], v[54:57], v[106:109], v[170:173]
	v_mfma_f32_16x16x32_bf16 v[154:157], v[42:45], v[130:133], v[154:157]
	v_mfma_f32_16x16x32_bf16 v[150:153], v[54:57], v[130:133], v[150:153]
	v_mfma_f32_16x16x32_bf16 v[126:129], v[42:45], v[146:149], v[126:129]
	v_mfma_f32_16x16x32_bf16 v[122:125], v[54:57], v[146:149], v[122:125]
	v_mfma_f32_16x16x32_bf16 v[178:181], v[42:45], v[98:101], v[194:197]
	v_mfma_f32_16x16x32_bf16 v[190:193], v[58:61], v[102:105], v[190:193]
	v_mfma_f32_16x16x32_bf16 v[174:177], v[46:49], v[118:121], v[174:177]
	v_mfma_f32_16x16x32_bf16 v[170:173], v[58:61], v[118:121], v[170:173]
	v_mfma_f32_16x16x32_bf16 v[154:157], v[46:49], v[138:141], v[154:157]
	v_mfma_f32_16x16x32_bf16 v[150:153], v[58:61], v[138:141], v[150:153]
	v_mfma_f32_16x16x32_bf16 v[126:129], v[46:49], v[158:161], v[126:129]
	v_mfma_f32_16x16x32_bf16 v[122:125], v[58:61], v[158:161], v[122:125]
	v_mfma_f32_16x16x32_bf16 v[178:181], v[46:49], v[102:105], v[178:181]
	s_setprio 0
	s_setprio 1
	v_mfma_f32_16x16x32_bf16 v[186:189], v[66:69], v[98:101], v[186:189]
	v_mfma_f32_16x16x32_bf16 v[98:101], v[74:77], v[98:101], v[182:185]
	v_mfma_f32_16x16x32_bf16 v[186:189], v[70:73], v[102:105], v[186:189]
	v_mfma_f32_16x16x32_bf16 v[98:101], v[78:81], v[102:105], v[98:101]
	v_mfma_f32_16x16x32_bf16 v[102:105], v[66:69], v[106:109], v[166:169]
	v_mfma_f32_16x16x32_bf16 v[106:109], v[74:77], v[106:109], v[162:165]
	v_mfma_f32_16x16x32_bf16 v[114:117], v[66:69], v[146:149], v[114:117]
	v_mfma_f32_16x16x32_bf16 v[110:113], v[74:77], v[146:149], v[110:113]
	v_mfma_f32_16x16x32_bf16 v[102:105], v[70:73], v[118:121], v[102:105]
	v_mfma_f32_16x16x32_bf16 v[106:109], v[78:81], v[118:121], v[106:109]
	v_mfma_f32_16x16x32_bf16 v[118:121], v[66:69], v[130:133], v[142:145]
	v_mfma_f32_16x16x32_bf16 v[130:133], v[74:77], v[130:133], v[134:137]
	v_mfma_f32_16x16x32_bf16 v[114:117], v[70:73], v[158:161], v[114:117]
	v_mfma_f32_16x16x32_bf16 v[110:113], v[78:81], v[158:161], v[110:113]
	v_mfma_f32_16x16x32_bf16 v[118:121], v[70:73], v[138:141], v[118:121]
	v_mfma_f32_16x16x32_bf16 v[130:133], v[78:81], v[138:141], v[130:133]
	s_setprio 0
	s_barrier
	s_add_i32 s14, s28, s4
	v_lshl_add_u64 v[208:209], s[36:37], 0, v[0:1]
	s_mov_b32 m0, s14
	ds_read_b128 v[134:137], v213 offset:16384
	ds_read_b128 v[138:141], v213 offset:17408
	ds_read_b128 v[142:145], v213 offset:18432
	ds_read_b128 v[146:149], v213 offset:19456
	ds_read_b128 v[158:161], v213 offset:20480
	ds_read_b128 v[162:165], v213 offset:21504
	ds_read_b128 v[166:169], v213 offset:22528
	ds_read_b128 v[182:185], v213 offset:23552
	global_load_lds_dwordx4 v[208:209], off
	s_add_i32 m0, s14, 0x2000
	s_add_u32 s62, s36, 0xb0000
	v_lshl_add_u64 v[228:229], s[36:37], 0, v[218:219]
	s_addc_u32 s63, s37, 0
	s_add_i32 s14, s72, s4
	global_load_lds_dwordx4 v[228:229], off
	v_lshl_add_u64 v[194:195], s[62:63], 0, v[0:1]
	s_mov_b32 m0, s14
	v_lshl_add_u64 v[230:231], s[90:91], 0, v[214:215]
	global_load_lds_dwordx4 v[194:195], off
	v_lshl_add_u64 v[194:195], s[62:63], 0, v[218:219]
	s_add_i32 m0, s14, 0x2000
	v_lshl_add_u64 v[232:233], s[90:91], 0, v[216:217]
	global_load_lds_dwordx4 v[194:195], off
	s_mov_b32 m0, s0
	s_nop 0
	global_load_lds_dwordx4 v[230:231], off
	s_mov_b32 m0, s1
	s_nop 0
	global_load_lds_dwordx4 v[232:233], off
	s_waitcnt vmcnt(8)
	s_waitcnt lgkmcnt(0)
	s_barrier
; #define PG8_STAGE(bufoff, gbase, voff) do { _Pragma("unroll") for (int _i = 0; _i < 2; ++_i) \
;         __builtin_amdgcn_global_load_lds((const unsigned*)((const char*)(gbase) + (voff)[_i]), (PG8_LAS unsigned*)(lds + (bufoff) + ldsw + _i * 8192), 16, 0, 0); } while (0)
; #define PG8_LDA(dst, b, h) do { _Pragma("unroll") for (int m = 0; m < 4; ++m) _Pragma("unroll") for (int k = 0; k < 2; ++k) dst[m][k] = *(const PG8_LAS bf16x8*)(lds + PG8_SA(b, h) + aoff + m * 2048 + k * 1024); } while (0)
; #define PG8_LDB(dst, b, h) do { _Pragma("unroll") for (int n = 0; n < 2; ++n) _Pragma("unroll") for (int k = 0; k < 2; ++k) dst[n][k] = *(const PG8_LAS bf16x8*)(lds + PG8_SB(b, h) + boff + n * 2048 + k * 1024); } while (0)
; #define PG8_MMA(ai, bj, At, Bt) do { __builtin_amdgcn_s_setprio(1); _Pragma("unroll") for (int m = 0; m < 4; ++m) _Pragma("unroll") for (int n = 0; n < 2; ++n) _Pragma("unroll") for (int k = 0; k < 2; ++k) \
;         acc[ai][bj][m][n] = mma16<Epi::F16>(Bt[n][k], At[m][k], acc[ai][bj][m][n]); __builtin_amdgcn_s_setprio(0); } while (0)
; #define PG8_WAIT_V(n) asm volatile("s_waitcnt vmcnt(" #n ")" ::: "memory")
; #define PG8_WAIT_L(n) asm volatile("s_waitcnt lgkmcnt(" #n ")" ::: "memory")
; #define PG8_BAR __builtin_amdgcn_s_barrier()
; #define PG8_SCHED __builtin_amdgcn_sched_barrier(0)
; template <class Epi, class Sched, bool ALIGN_EPI = false, bool SP2 = false>
; __device__ __forceinline__ void gemm_phase(PG8_LAS unsigned char* lds, const Gemm g, const Sched& S, const Epi& E, const int wave_in) {
;     ...
;             PG8_WAIT_V(8); PG8_WAIT_L(0); PG8_BAR; PG8_MMA(1, 0, At, B0); PG8_MMA(1, 1, At, B1); PG8_BAR; PG8_SCHED;
;             PG8_LDB(B0, 1, 0); PG8_LDB(B1, 1, 1); PG8_SCHED; PG8_LDA(At, 1, 0); PG8_STAGE(PG8_SA(0, 1), a2 + hstep, voffA);
;             PG8_WAIT_V(8); PG8_WAIT_L(0); PG8_BAR; PG8_MMA(0, 0, At, B0); PG8_MMA(0, 1, At, B1); PG8_BAR; PG8_SCHED;
	s_setprio 1
	s_waitcnt lgkmcnt(0)
	v_mfma_f32_16x16x32_bf16 v[94:97], v[42:45], v[134:137], v[94:97]
	v_mfma_f32_16x16x32_bf16 v[90:93], v[54:57], v[134:137], v[90:93]
	v_mfma_f32_16x16x32_bf16 v[62:65], v[42:45], v[142:145], v[62:65]
	v_mfma_f32_16x16x32_bf16 v[50:53], v[54:57], v[142:145], v[50:53]
	v_mfma_f32_16x16x32_bf16 v[30:33], v[42:45], v[158:161], v[30:33]
	v_mfma_f32_16x16x32_bf16 v[26:29], v[54:57], v[158:161], v[26:29]
	v_mfma_f32_16x16x32_bf16 v[14:17], v[42:45], v[166:169], v[14:17]
	v_mfma_f32_16x16x32_bf16 v[10:13], v[54:57], v[166:169], v[10:13]
	v_mfma_f32_16x16x32_bf16 v[94:97], v[46:49], v[138:141], v[94:97]
	v_mfma_f32_16x16x32_bf16 v[90:93], v[58:61], v[138:141], v[90:93]
	v_mfma_f32_16x16x32_bf16 v[62:65], v[46:49], v[146:149], v[62:65]
	v_mfma_f32_16x16x32_bf16 v[50:53], v[58:61], v[146:149], v[50:53]
	v_mfma_f32_16x16x32_bf16 v[30:33], v[46:49], v[162:165], v[30:33]
	v_mfma_f32_16x16x32_bf16 v[26:29], v[58:61], v[162:165], v[26:29]
	v_mfma_f32_16x16x32_bf16 v[14:17], v[46:49], v[182:185], v[14:17]
	v_mfma_f32_16x16x32_bf16 v[10:13], v[58:61], v[182:185], v[10:13]
	s_setprio 0
	s_setprio 1
	v_mfma_f32_16x16x32_bf16 v[38:41], v[66:69], v[142:145], v[38:41]
	v_mfma_f32_16x16x32_bf16 v[34:37], v[74:77], v[142:145], v[34:37]
	v_mfma_f32_16x16x32_bf16 v[22:25], v[66:69], v[158:161], v[22:25]
	v_mfma_f32_16x16x32_bf16 v[18:21], v[74:77], v[158:161], v[18:21]
	v_mfma_f32_16x16x32_bf16 v[6:9], v[66:69], v[166:169], v[6:9]
	v_mfma_f32_16x16x32_bf16 v[2:5], v[74:77], v[166:169], v[2:5]
	v_mfma_f32_16x16x32_bf16 v[42:45], v[66:69], v[134:137], v[86:89]
	v_mfma_f32_16x16x32_bf16 v[46:49], v[74:77], v[134:137], v[82:85]
	v_mfma_f32_16x16x32_bf16 v[38:41], v[70:73], v[146:149], v[38:41]
	v_mfma_f32_16x16x32_bf16 v[34:37], v[78:81], v[146:149], v[34:37]
	v_mfma_f32_16x16x32_bf16 v[22:25], v[70:73], v[162:165], v[22:25]
	v_mfma_f32_16x16x32_bf16 v[18:21], v[78:81], v[162:165], v[18:21]
	v_mfma_f32_16x16x32_bf16 v[6:9], v[70:73], v[182:185], v[6:9]
	v_mfma_f32_16x16x32_bf16 v[2:5], v[78:81], v[182:185], v[2:5]
	v_mfma_f32_16x16x32_bf16 v[42:45], v[70:73], v[138:141], v[42:45]
	v_mfma_f32_16x16x32_bf16 v[46:49], v[78:81], v[138:141], v[46:49]
	s_setprio 0
	s_barrier
	v_add_u32_e32 v70, s73, v211
	v_add_u32_e32 v82, s74, v211
	ds_read_b128 v[54:57], v70
	ds_read_b128 v[58:61], v70 offset:1024
	ds_read_b128 v[66:69], v70 offset:2048
	ds_read_b128 v[70:73], v70 offset:3072
	ds_read_b128 v[74:77], v82
	ds_read_b128 v[78:81], v82 offset:1024
	ds_read_b128 v[138:141], v82 offset:2048
	ds_read_b128 v[146:149], v82 offset:3072
	s_add_u32 s62, s90, 0xb0000
	s_addc_u32 s63, s91, 0
	s_mov_b32 m0, s5
	v_lshl_add_u64 v[162:163], s[62:63], 0, v[214:215]
	ds_read_b128 v[82:85], v213 offset:32768
	ds_read_b128 v[86:89], v213 offset:33792
	ds_read_b128 v[134:137], v213 offset:34816
	ds_read_b128 v[142:145], v213 offset:35840
	ds_read_b128 v[158:161], v213 offset:36864
	ds_read_b128 v[198:201], v213 offset:37888
	ds_read_b128 v[202:205], v213 offset:38912
	ds_read_b128 v[224:227], v213 offset:39936
	global_load_lds_dwordx4 v[162:163], off
	v_lshl_add_u64 v[162:163], s[62:63], 0, v[216:217]
	s_mov_b32 m0, s82
	s_nop 0
	global_load_lds_dwordx4 v[162:163], off
	s_waitcnt vmcnt(8)
	s_waitcnt lgkmcnt(0)
	s_barrier
	s_setprio 1
	s_waitcnt lgkmcnt(0)
	v_mfma_f32_16x16x32_bf16 v[162:165], v[54:57], v[82:85], v[178:181]
	v_mfma_f32_16x16x32_bf16 v[194:197], v[58:61], v[86:89], v[162:165]
	v_mfma_f32_16x16x32_bf16 v[162:165], v[66:69], v[82:85], v[190:193]
	v_mfma_f32_16x16x32_bf16 v[190:193], v[70:73], v[86:89], v[162:165]
	v_mfma_f32_16x16x32_bf16 v[162:165], v[54:57], v[134:137], v[174:177]
	v_mfma_f32_16x16x32_bf16 v[174:177], v[58:61], v[142:145], v[162:165]
	v_mfma_f32_16x16x32_bf16 v[162:165], v[66:69], v[134:137], v[170:173]
	v_mfma_f32_16x16x32_bf16 v[154:157], v[54:57], v[158:161], v[154:157]
	v_mfma_f32_16x16x32_bf16 v[150:153], v[66:69], v[158:161], v[150:153]
	v_mfma_f32_16x16x32_bf16 v[126:129], v[54:57], v[202:205], v[126:129]
	v_mfma_f32_16x16x32_bf16 v[122:125], v[66:69], v[202:205], v[122:125]
	v_mfma_f32_16x16x32_bf16 v[170:173], v[70:73], v[142:145], v[162:165]
	v_mfma_f32_16x16x32_bf16 v[154:157], v[58:61], v[198:201], v[154:157]
	v_mfma_f32_16x16x32_bf16 v[150:153], v[70:73], v[198:201], v[150:153]
	v_mfma_f32_16x16x32_bf16 v[126:129], v[58:61], v[224:227], v[126:129]
	v_mfma_f32_16x16x32_bf16 v[122:125], v[70:73], v[224:227], v[122:125]
	s_setprio 0
	s_setprio 1
	v_mfma_f32_16x16x32_bf16 v[162:165], v[74:77], v[82:85], v[186:189]
	v_mfma_f32_16x16x32_bf16 v[82:85], v[138:141], v[82:85], v[98:101]
	v_mfma_f32_16x16x32_bf16 v[182:185], v[146:149], v[86:89], v[82:85]
	v_mfma_f32_16x16x32_bf16 v[82:85], v[74:77], v[134:137], v[102:105]
	v_mfma_f32_16x16x32_bf16 v[166:169], v[78:81], v[142:145], v[82:85]
	v_mfma_f32_16x16x32_bf16 v[82:85], v[138:141], v[134:137], v[106:109]
	v_mfma_f32_16x16x32_bf16 v[186:189], v[78:81], v[86:89], v[162:165]
	v_mfma_f32_16x16x32_bf16 v[162:165], v[146:149], v[142:145], v[82:85]
	v_mfma_f32_16x16x32_bf16 v[82:85], v[74:77], v[158:161], v[118:121]
	v_mfma_f32_16x16x32_bf16 v[142:145], v[78:81], v[198:201], v[82:85]
	v_mfma_f32_16x16x32_bf16 v[82:85], v[138:141], v[158:161], v[130:133]
	v_mfma_f32_16x16x32_bf16 v[134:137], v[146:149], v[198:201], v[82:85]
	v_mfma_f32_16x16x32_bf16 v[82:85], v[74:77], v[202:205], v[114:117]
	v_mfma_f32_16x16x32_bf16 v[114:117], v[78:81], v[224:227], v[82:85]
	v_mfma_f32_16x16x32_bf16 v[82:85], v[138:141], v[202:205], v[110:113]
	v_mfma_f32_16x16x32_bf16 v[110:113], v[146:149], v[224:227], v[82:85]
	s_setprio 0
	s_barrier
; #define PG8_STAGE(bufoff, gbase, voff) do { _Pragma("unroll") for (int _i = 0; _i < 2; ++_i) \
;         __builtin_amdgcn_global_load_lds((const unsigned*)((const char*)(gbase) + (voff)[_i]), (PG8_LAS unsigned*)(lds + (bufoff) + ldsw + _i * 8192), 16, 0, 0); } while (0)
; #define PG8_LDA(dst, b, h) do { _Pragma("unroll") for (int m = 0; m < 4; ++m) _Pragma("unroll") for (int k = 0; k < 2; ++k) dst[m][k] = *(const PG8_LAS bf16x8*)(lds + PG8_SA(b, h) + aoff + m * 2048 + k * 1024); } while (0)
; #define PG8_MMA(ai, bj, At, Bt) do { __builtin_amdgcn_s_setprio(1); _Pragma("unroll") for (int m = 0; m < 4; ++m) _Pragma("unroll") for (int n = 0; n < 2; ++n) _Pragma("unroll") for (int k = 0; k < 2; ++k) \
;         acc[ai][bj][m][n] = mma16<Epi::F16>(Bt[n][k], At[m][k], acc[ai][bj][m][n]); __builtin_amdgcn_s_setprio(0); } while (0)
; #define PG8_WAIT_V(n) asm volatile("s_waitcnt vmcnt(" #n ")" ::: "memory")
; #define PG8_WAIT_L(n) asm volatile("s_waitcnt lgkmcnt(" #n ")" ::: "memory")
; #define PG8_BAR __builtin_amdgcn_s_barrier()
; #define PG8_SCHED __builtin_amdgcn_sched_barrier(0)
; template <class Epi, class Sched, bool ALIGN_EPI = false, bool SP2 = false>
; __device__ __forceinline__ void gemm_phase(PG8_LAS unsigned char* lds, const Gemm g, const Sched& S, const Epi& E, const int wave_in) {
;     ...
;         for (int t = 0; t < nt; t += 2) {
;             const bool last = (t == nt - 2);
;             const char* a1 = cA + (size_t)(t + 1) * kstep;
;             const char* a2 = last ? nA : cA + (size_t)(t + 2) * kstep; const char* b2 = last ? nB : cB + (size_t)(t + 2) * kstep;
;             const char* a3 = a2 + kstep; const char* b3 = b2 + kstep;
;             if (last && has_next) S.a_ready(nxt);
;     ...
;             PG8_LDA(At, 1, 1); PG8_STAGE(PG8_SB(1, 0), b3, voffB); PG8_STAGE(PG8_SB(1, 1), b3 + hstep, voffB); PG8_STAGE(PG8_SA(1, 0), a3, voffA);
;             PG8_WAIT_V(8); PG8_WAIT_L(0); PG8_BAR; PG8_MMA(1, 0, At, B0); PG8_MMA(1, 1, At, B1); PG8_BAR; PG8_SCHED;
	s_add_i32 s14, s73, s4
	v_lshl_add_u64 v[86:87], v[208:209], 0, s[78:79]
	s_mov_b32 m0, s14
	s_nop 1
	ds_read_b128 v[82:85], v213 offset:49152
	ds_read_b128 v[98:101], v213 offset:50176
	ds_read_b128 v[102:105], v213 offset:51200
	ds_read_b128 v[106:109], v213 offset:52224
	ds_read_b128 v[118:121], v213 offset:53248
	ds_read_b128 v[130:133], v213 offset:54272
	ds_read_b128 v[158:161], v213 offset:55296
	ds_read_b128 v[178:181], v213 offset:56320
	global_load_lds_dwordx4 v[86:87], off
	s_add_i32 m0, s14, 0x2000
	s_add_u32 s36, s36, 0xb0080
	v_lshl_add_u64 v[86:87], v[228:229], 0, s[78:79]
	s_addc_u32 s37, s37, 0
	s_add_i32 s14, s74, s4
	global_load_lds_dwordx4 v[86:87], off
	v_lshl_add_u64 v[86:87], s[36:37], 0, v[0:1]
	s_mov_b32 m0, s14
	s_nop 0
	global_load_lds_dwordx4 v[86:87], off
	v_lshl_add_u64 v[86:87], s[36:37], 0, v[218:219]
	s_add_i32 m0, s14, 0x2000
	s_nop 0
	global_load_lds_dwordx4 v[86:87], off
	v_lshl_add_u64 v[86:87], v[230:231], 0, s[78:79]
	s_mov_b32 m0, s71
	s_nop 0
	global_load_lds_dwordx4 v[86:87], off
	v_lshl_add_u64 v[86:87], v[232:233], 0, s[78:79]
	s_mov_b32 m0, s6
	s_nop 0
	global_load_lds_dwordx4 v[86:87], off
	s_waitcnt vmcnt(8)
	s_waitcnt lgkmcnt(0)
	s_barrier
	s_setprio 1
	s_waitcnt lgkmcnt(0)
	v_mfma_f32_16x16x32_bf16 v[86:89], v[54:57], v[82:85], v[94:97]
	v_mfma_f32_16x16x32_bf16 v[94:97], v[58:61], v[98:101], v[86:89]
	v_mfma_f32_16x16x32_bf16 v[86:89], v[66:69], v[82:85], v[90:93]
	v_mfma_f32_16x16x32_bf16 v[62:65], v[54:57], v[102:105], v[62:65]
	v_mfma_f32_16x16x32_bf16 v[50:53], v[66:69], v[102:105], v[50:53]
	v_mfma_f32_16x16x32_bf16 v[30:33], v[54:57], v[118:121], v[30:33]
	v_mfma_f32_16x16x32_bf16 v[26:29], v[66:69], v[118:121], v[26:29]
	v_mfma_f32_16x16x32_bf16 v[14:17], v[54:57], v[158:161], v[14:17]
	v_mfma_f32_16x16x32_bf16 v[10:13], v[66:69], v[158:161], v[10:13]
	v_mfma_f32_16x16x32_bf16 v[90:93], v[70:73], v[98:101], v[86:89]
	v_mfma_f32_16x16x32_bf16 v[62:65], v[58:61], v[106:109], v[62:65]
	v_mfma_f32_16x16x32_bf16 v[50:53], v[70:73], v[106:109], v[50:53]
	v_mfma_f32_16x16x32_bf16 v[30:33], v[58:61], v[130:133], v[30:33]
	v_mfma_f32_16x16x32_bf16 v[26:29], v[70:73], v[130:133], v[26:29]
	v_mfma_f32_16x16x32_bf16 v[14:17], v[58:61], v[178:181], v[14:17]
	v_mfma_f32_16x16x32_bf16 v[10:13], v[70:73], v[178:181], v[10:13]
	s_setprio 0
	s_setprio 1
	v_mfma_f32_16x16x32_bf16 v[42:45], v[74:77], v[82:85], v[42:45]
	v_mfma_f32_16x16x32_bf16 v[86:89], v[78:81], v[98:101], v[42:45]
	v_mfma_f32_16x16x32_bf16 v[42:45], v[138:141], v[82:85], v[46:49]
	v_mfma_f32_16x16x32_bf16 v[38:41], v[74:77], v[102:105], v[38:41]
	v_mfma_f32_16x16x32_bf16 v[34:37], v[138:141], v[102:105], v[34:37]
	v_mfma_f32_16x16x32_bf16 v[22:25], v[74:77], v[118:121], v[22:25]
	v_mfma_f32_16x16x32_bf16 v[18:21], v[138:141], v[118:121], v[18:21]
	v_mfma_f32_16x16x32_bf16 v[6:9], v[74:77], v[158:161], v[6:9]
	v_mfma_f32_16x16x32_bf16 v[2:5], v[138:141], v[158:161], v[2:5]
	v_mfma_f32_16x16x32_bf16 v[82:85], v[146:149], v[98:101], v[42:45]
	v_mfma_f32_16x16x32_bf16 v[38:41], v[78:81], v[106:109], v[38:41]
	v_mfma_f32_16x16x32_bf16 v[34:37], v[146:149], v[106:109], v[34:37]
	v_mfma_f32_16x16x32_bf16 v[22:25], v[78:81], v[130:133], v[22:25]
	v_mfma_f32_16x16x32_bf16 v[18:21], v[146:149], v[130:133], v[18:21]
	v_mfma_f32_16x16x32_bf16 v[6:9], v[78:81], v[178:181], v[6:9]
	v_mfma_f32_16x16x32_bf16 v[2:5], v[146:149], v[178:181], v[2:5]
	s_setprio 0
	s_add_i32 s13, s13, 2
	s_add_u32 s11, s11, 0x100
	s_addc_u32 s12, s12, 0
	s_cmp_gt_u32 s13, 41
	s_mov_b64 s[62:63], s[86:87]
	s_barrier
	s_cbranch_scc0 .LBB0_418
	s_and_b64 vcc, exec, s[58:59]
	s_cbranch_vccz .LBB0_421
	s_barrier

; #define PG8_STAGE(bufoff, gbase, voff) do { _Pragma("unroll") for (int _i = 0; _i < 2; ++_i) \
;         __builtin_amdgcn_global_load_lds((const unsigned*)((const char*)(gbase) + (voff)[_i]), (PG8_LAS unsigned*)(lds + (bufoff) + ldsw + _i * 8192), 16, 0, 0); } while (0)
; #define PG8_LDA(dst, b, h) do { _Pragma("unroll") for (int m = 0; m < 4; ++m) _Pragma("unroll") for (int k = 0; k < 2; ++k) dst[m][k] = *(const PG8_LAS bf16x8*)(lds + PG8_SA(b, h) + aoff + m * 2048 + k * 1024); } while (0)
; #define PG8_LDB(dst, b, h) do { _Pragma("unroll") for (int n = 0; n < 2; ++n) _Pragma("unroll") for (int k = 0; k < 2; ++k) dst[n][k] = *(const PG8_LAS bf16x8*)(lds + PG8_SB(b, h) + boff + n * 2048 + k * 1024); } while (0)
; #define PG8_MMA(ai, bj, At, Bt) do { __builtin_amdgcn_s_setprio(1); _Pragma("unroll") for (int m = 0; m < 4; ++m) _Pragma("unroll") for (int n = 0; n < 2; ++n) _Pragma("unroll") for (int k = 0; k < 2; ++k) \
;         acc[ai][bj][m][n] = mma16<Epi::F16>(Bt[n][k], At[m][k], acc[ai][bj][m][n]); __builtin_amdgcn_s_setprio(0); } while (0)
; #define PG8_WAIT_V(n) asm volatile("s_waitcnt vmcnt(" #n ")" ::: "memory")
; #define PG8_WAIT_L(n) asm volatile("s_waitcnt lgkmcnt(" #n ")" ::: "memory")
; template <class Epi, class Sched, bool ALIGN_EPI = false, bool SP2 = false>
; __device__ __forceinline__ void gemm_phase(PG8_LAS unsigned char* lds, const Gemm g, const Sched& S, const Epi& E, const int wave_in) {
;     ...
;         for (int t = 0; t < nt; t += 2) {
;             const bool last = (t == nt - 2);
;             const char* a1 = cA + (size_t)(t + 1) * kstep;
;             const char* a2 = last ? nA : cA + (size_t)(t + 2) * kstep; const char* b2 = last ? nB : cB + (size_t)(t + 2) * kstep;
;             const char* a3 = a2 + kstep; const char* b3 = b2 + kstep;
;             if (last && has_next) S.a_ready(nxt);
;             if constexpr (SP2) {
;             PG8_LDB(B0, 0, 0); PG8_LDB(B1, 0, 1); PG8_SCHED; PG8_LDA(At, 0, 0); PG8_STAGE(PG8_SA(1, 1), a1 + hstep, voffA);
;             PG8_WAIT_V(8); PG8_WAIT_L(0); PG8_BAR; PG8_MMA(0, 0, At, B0); PG8_MMA(0, 1, At, B1); PG8_BAR; PG8_SCHED;
;             PG8_LDA(At, 0, 1); PG8_STAGE(PG8_SB(0, 0), b2, voffB); PG8_STAGE(PG8_SB(0, 1), b2 + hstep, voffB); PG8_STAGE(PG8_SA(0, 0), a2, voffA);
;             PG8_WAIT_V(8); PG8_WAIT_L(0); PG8_BAR; PG8_MMA(1, 0, At, B0); PG8_MMA(1, 1, At, B1); PG8_BAR; PG8_SCHED;
.LBB0_594:
	v_add_u32_e32 v58, s28, v210
	v_add_u32_e32 v86, s72, v210
	ds_read_b128 v[42:45], v58
	ds_read_b128 v[46:49], v58 offset:1024
	ds_read_b128 v[54:57], v58 offset:2048
	ds_read_b128 v[58:61], v58 offset:3072
	ds_read_b128 v[74:77], v86
	ds_read_b128 v[78:81], v86 offset:1024
	ds_read_b128 v[82:85], v86 offset:2048
	ds_read_b128 v[86:89], v86 offset:3072
	s_add_u32 s13, s38, 0xfffc0080
	s_addc_u32 s14, s39, -1
	s_cmp_eq_u32 s12, 12
	s_cselect_b32 s43, s9, s14
	s_cselect_b32 s42, s10, s13
	s_cselect_b32 s37, s11, s59
	s_cselect_b32 s36, s44, s45
	v_lshl_add_u64 v[212:213], s[38:39], 0, v[186:187]
	s_add_i32 m0, s83, 0xc000
	ds_read_b128 v[162:165], v229
	ds_read_b128 v[166:169], v229 offset:1024
	ds_read_b128 v[170:173], v229 offset:2048
	ds_read_b128 v[174:177], v229 offset:3072
	ds_read_b128 v[190:193], v229 offset:4096
	ds_read_b128 v[194:197], v229 offset:5120
	ds_read_b128 v[198:201], v229 offset:6144
	ds_read_b128 v[202:205], v229 offset:7168
	global_load_lds_dwordx4 v[212:213], off
	v_lshl_add_u64 v[212:213], s[38:39], 0, v[188:189]
	s_add_i32 m0, s83, 0xe000
	s_nop 0
	global_load_lds_dwordx4 v[212:213], off
	s_waitcnt vmcnt(8)
	s_waitcnt lgkmcnt(0)
	s_barrier
	s_setprio 1
	s_waitcnt lgkmcnt(0)
	v_mfma_f32_16x16x32_f16 v[158:161], v[42:45], v[162:165], v[158:161]
	v_mfma_f32_16x16x32_f16 v[154:157], v[54:57], v[162:165], v[154:157]
	v_mfma_f32_16x16x32_f16 v[142:145], v[42:45], v[170:173], v[142:145]
	v_mfma_f32_16x16x32_f16 v[138:141], v[54:57], v[170:173], v[138:141]
	v_mfma_f32_16x16x32_f16 v[126:129], v[42:45], v[190:193], v[126:129]
	v_mfma_f32_16x16x32_f16 v[122:125], v[54:57], v[190:193], v[122:125]
	v_mfma_f32_16x16x32_f16 v[110:113], v[42:45], v[198:201], v[110:113]
	v_mfma_f32_16x16x32_f16 v[106:109], v[54:57], v[198:201], v[106:109]
	v_mfma_f32_16x16x32_f16 v[158:161], v[46:49], v[166:169], v[158:161]
	v_mfma_f32_16x16x32_f16 v[154:157], v[58:61], v[166:169], v[154:157]
	v_mfma_f32_16x16x32_f16 v[142:145], v[46:49], v[174:177], v[142:145]
	v_mfma_f32_16x16x32_f16 v[138:141], v[58:61], v[174:177], v[138:141]
	v_mfma_f32_16x16x32_f16 v[126:129], v[46:49], v[194:197], v[126:129]
	v_mfma_f32_16x16x32_f16 v[122:125], v[58:61], v[194:197], v[122:125]
	v_mfma_f32_16x16x32_f16 v[110:113], v[46:49], v[202:205], v[110:113]
	v_mfma_f32_16x16x32_f16 v[106:109], v[58:61], v[202:205], v[106:109]
	s_setprio 0
	s_setprio 1
	v_mfma_f32_16x16x32_f16 v[150:153], v[74:77], v[162:165], v[150:153]
	v_mfma_f32_16x16x32_f16 v[146:149], v[82:85], v[162:165], v[146:149]
	v_mfma_f32_16x16x32_f16 v[134:137], v[74:77], v[170:173], v[134:137]
	v_mfma_f32_16x16x32_f16 v[130:133], v[82:85], v[170:173], v[130:133]
	v_mfma_f32_16x16x32_f16 v[118:121], v[74:77], v[190:193], v[118:121]
	v_mfma_f32_16x16x32_f16 v[114:117], v[82:85], v[190:193], v[114:117]
	v_mfma_f32_16x16x32_f16 v[102:105], v[74:77], v[198:201], v[102:105]
	v_mfma_f32_16x16x32_f16 v[98:101], v[82:85], v[198:201], v[98:101]
	v_mfma_f32_16x16x32_f16 v[150:153], v[78:81], v[166:169], v[150:153]
	v_mfma_f32_16x16x32_f16 v[146:149], v[86:89], v[166:169], v[146:149]
	v_mfma_f32_16x16x32_f16 v[134:137], v[78:81], v[174:177], v[134:137]
	v_mfma_f32_16x16x32_f16 v[130:133], v[86:89], v[174:177], v[130:133]
	v_mfma_f32_16x16x32_f16 v[118:121], v[78:81], v[194:197], v[118:121]
	v_mfma_f32_16x16x32_f16 v[114:117], v[86:89], v[194:197], v[114:117]
	v_mfma_f32_16x16x32_f16 v[102:105], v[78:81], v[202:205], v[102:105]
	v_mfma_f32_16x16x32_f16 v[98:101], v[86:89], v[202:205], v[98:101]
	s_setprio 0
	s_barrier
	s_add_i32 s13, s28, s82
	v_lshl_add_u64 v[212:213], s[36:37], 0, v[0:1]
	s_mov_b32 m0, s13
	ds_read_b128 v[162:165], v229 offset:16384
	ds_read_b128 v[166:169], v229 offset:17408
	ds_read_b128 v[170:173], v229 offset:18432
	ds_read_b128 v[174:177], v229 offset:19456
	ds_read_b128 v[190:193], v229 offset:20480
	ds_read_b128 v[194:197], v229 offset:21504
	ds_read_b128 v[198:201], v229 offset:22528
	ds_read_b128 v[202:205], v229 offset:23552
	global_load_lds_dwordx4 v[212:213], off
	s_add_i32 m0, s13, 0x2000
	s_add_u32 vcc_lo, s36, 0x40000
	v_lshl_add_u64 v[214:215], s[36:37], 0, v[182:183]
	s_addc_u32 vcc_hi, s37, 0
	s_add_i32 s13, s72, s82
	global_load_lds_dwordx4 v[214:215], off
	v_lshl_add_u64 v[216:217], vcc, 0, v[0:1]
	s_mov_b32 m0, s13
	v_lshl_add_u64 v[218:219], s[42:43], 0, v[180:181]
	global_load_lds_dwordx4 v[216:217], off
	v_lshl_add_u64 v[216:217], vcc, 0, v[182:183]
	s_add_i32 m0, s13, 0x2000
	s_nop 0
	global_load_lds_dwordx4 v[216:217], off
	v_lshl_add_u64 v[216:217], s[42:43], 0, v[178:179]
	s_mov_b32 m0, s83
	s_nop 0
	global_load_lds_dwordx4 v[216:217], off
	s_mov_b32 m0, s4
	s_nop 0
	global_load_lds_dwordx4 v[218:219], off
	s_waitcnt vmcnt(8)
	s_waitcnt lgkmcnt(0)
	s_barrier
; #define PG8_STAGE(bufoff, gbase, voff) do { _Pragma("unroll") for (int _i = 0; _i < 2; ++_i) \
;         __builtin_amdgcn_global_load_lds((const unsigned*)((const char*)(gbase) + (voff)[_i]), (PG8_LAS unsigned*)(lds + (bufoff) + ldsw + _i * 8192), 16, 0, 0); } while (0)
; #define PG8_LDA(dst, b, h) do { _Pragma("unroll") for (int m = 0; m < 4; ++m) _Pragma("unroll") for (int k = 0; k < 2; ++k) dst[m][k] = *(const PG8_LAS bf16x8*)(lds + PG8_SA(b, h) + aoff + m * 2048 + k * 1024); } while (0)
; #define PG8_LDB(dst, b, h) do { _Pragma("unroll") for (int n = 0; n < 2; ++n) _Pragma("unroll") for (int k = 0; k < 2; ++k) dst[n][k] = *(const PG8_LAS bf16x8*)(lds + PG8_SB(b, h) + boff + n * 2048 + k * 1024); } while (0)
; #define PG8_MMA(ai, bj, At, Bt) do { __builtin_amdgcn_s_setprio(1); _Pragma("unroll") for (int m = 0; m < 4; ++m) _Pragma("unroll") for (int n = 0; n < 2; ++n) _Pragma("unroll") for (int k = 0; k < 2; ++k) \
;         acc[ai][bj][m][n] = mma16<Epi::F16>(Bt[n][k], At[m][k], acc[ai][bj][m][n]); __builtin_amdgcn_s_setprio(0); } while (0)
; #define PG8_WAIT_V(n) asm volatile("s_waitcnt vmcnt(" #n ")" ::: "memory")
; #define PG8_WAIT_L(n) asm volatile("s_waitcnt lgkmcnt(" #n ")" ::: "memory")
; #define PG8_BAR __builtin_amdgcn_s_barrier()
; #define PG8_SCHED __builtin_amdgcn_sched_barrier(0)
; template <class Epi, class Sched, bool ALIGN_EPI = false, bool SP2 = false>
; __device__ __forceinline__ void gemm_phase(PG8_LAS unsigned char* lds, const Gemm g, const Sched& S, const Epi& E, const int wave_in) {
;     ...
;             PG8_WAIT_V(8); PG8_WAIT_L(0); PG8_BAR; PG8_MMA(1, 0, At, B0); PG8_MMA(1, 1, At, B1); PG8_BAR; PG8_SCHED;
;             PG8_LDB(B0, 1, 0); PG8_LDB(B1, 1, 1); PG8_SCHED; PG8_LDA(At, 1, 0); PG8_STAGE(PG8_SA(0, 1), a2 + hstep, voffA);
;             PG8_WAIT_V(8); PG8_WAIT_L(0); PG8_BAR; PG8_MMA(0, 0, At, B0); PG8_MMA(0, 1, At, B1); PG8_BAR; PG8_SCHED;
	s_setprio 1
	s_waitcnt lgkmcnt(0)
	v_mfma_f32_16x16x32_f16 v[94:97], v[42:45], v[162:165], v[94:97]
	v_mfma_f32_16x16x32_f16 v[90:93], v[54:57], v[162:165], v[90:93]
	v_mfma_f32_16x16x32_f16 v[62:65], v[42:45], v[170:173], v[62:65]
	v_mfma_f32_16x16x32_f16 v[50:53], v[54:57], v[170:173], v[50:53]
	v_mfma_f32_16x16x32_f16 v[30:33], v[42:45], v[190:193], v[30:33]
	v_mfma_f32_16x16x32_f16 v[26:29], v[54:57], v[190:193], v[26:29]
	v_mfma_f32_16x16x32_f16 v[14:17], v[42:45], v[198:201], v[14:17]
	v_mfma_f32_16x16x32_f16 v[10:13], v[54:57], v[198:201], v[10:13]
	v_mfma_f32_16x16x32_f16 v[94:97], v[46:49], v[166:169], v[94:97]
	v_mfma_f32_16x16x32_f16 v[90:93], v[58:61], v[166:169], v[90:93]
	v_mfma_f32_16x16x32_f16 v[62:65], v[46:49], v[174:177], v[62:65]
	v_mfma_f32_16x16x32_f16 v[50:53], v[58:61], v[174:177], v[50:53]
	v_mfma_f32_16x16x32_f16 v[30:33], v[46:49], v[194:197], v[30:33]
	v_mfma_f32_16x16x32_f16 v[26:29], v[58:61], v[194:197], v[26:29]
	v_mfma_f32_16x16x32_f16 v[14:17], v[46:49], v[202:205], v[14:17]
	v_mfma_f32_16x16x32_f16 v[10:13], v[58:61], v[202:205], v[10:13]
	s_setprio 0
	s_setprio 1
	v_mfma_f32_16x16x32_f16 v[38:41], v[74:77], v[170:173], v[38:41]
	v_mfma_f32_16x16x32_f16 v[34:37], v[82:85], v[170:173], v[34:37]
	v_mfma_f32_16x16x32_f16 v[22:25], v[74:77], v[190:193], v[22:25]
	v_mfma_f32_16x16x32_f16 v[18:21], v[82:85], v[190:193], v[18:21]
	v_mfma_f32_16x16x32_f16 v[6:9], v[74:77], v[198:201], v[6:9]
	v_mfma_f32_16x16x32_f16 v[2:5], v[82:85], v[198:201], v[2:5]
	v_mfma_f32_16x16x32_f16 v[42:45], v[74:77], v[162:165], v[70:73]
	v_mfma_f32_16x16x32_f16 v[46:49], v[82:85], v[162:165], v[66:69]
	v_mfma_f32_16x16x32_f16 v[38:41], v[78:81], v[174:177], v[38:41]
	v_mfma_f32_16x16x32_f16 v[34:37], v[86:89], v[174:177], v[34:37]
	v_mfma_f32_16x16x32_f16 v[22:25], v[78:81], v[194:197], v[22:25]
	v_mfma_f32_16x16x32_f16 v[18:21], v[86:89], v[194:197], v[18:21]
	v_mfma_f32_16x16x32_f16 v[6:9], v[78:81], v[202:205], v[6:9]
	v_mfma_f32_16x16x32_f16 v[2:5], v[86:89], v[202:205], v[2:5]
	v_mfma_f32_16x16x32_f16 v[42:45], v[78:81], v[166:169], v[42:45]
	v_mfma_f32_16x16x32_f16 v[46:49], v[86:89], v[166:169], v[46:49]
	s_setprio 0
	s_barrier
	v_add_u32_e32 v70, s73, v210
	v_add_u32_e32 v86, s74, v210
	ds_read_b128 v[54:57], v70
	ds_read_b128 v[58:61], v70 offset:1024
	ds_read_b128 v[66:69], v70 offset:2048
	ds_read_b128 v[70:73], v70 offset:3072
	ds_read_b128 v[74:77], v86
	ds_read_b128 v[78:81], v86 offset:1024
	ds_read_b128 v[82:85], v86 offset:2048
	ds_read_b128 v[86:89], v86 offset:3072
	s_add_u32 s42, s42, 0x40000
	s_addc_u32 s43, s43, 0
	s_mov_b32 m0, s5
	v_lshl_add_u64 v[220:221], s[42:43], 0, v[178:179]
	ds_read_b128 v[162:165], v229 offset:32768
	ds_read_b128 v[166:169], v229 offset:33792
	ds_read_b128 v[170:173], v229 offset:34816
	ds_read_b128 v[174:177], v229 offset:35840
	ds_read_b128 v[190:193], v229 offset:36864
	ds_read_b128 v[194:197], v229 offset:37888
	ds_read_b128 v[198:201], v229 offset:38912
	ds_read_b128 v[202:205], v229 offset:39936
	global_load_lds_dwordx4 v[220:221], off
	v_lshl_add_u64 v[220:221], s[42:43], 0, v[180:181]
	s_mov_b32 m0, s0
	s_nop 0
	global_load_lds_dwordx4 v[220:221], off
	s_waitcnt vmcnt(8)
	s_waitcnt lgkmcnt(0)
	s_barrier
	s_setprio 1
	s_waitcnt lgkmcnt(0)
	v_mfma_f32_16x16x32_f16 v[158:161], v[54:57], v[162:165], v[158:161]
	v_mfma_f32_16x16x32_f16 v[154:157], v[66:69], v[162:165], v[154:157]
	v_mfma_f32_16x16x32_f16 v[142:145], v[54:57], v[170:173], v[142:145]
	v_mfma_f32_16x16x32_f16 v[138:141], v[66:69], v[170:173], v[138:141]
	v_mfma_f32_16x16x32_f16 v[126:129], v[54:57], v[190:193], v[126:129]
	v_mfma_f32_16x16x32_f16 v[122:125], v[66:69], v[190:193], v[122:125]
	v_mfma_f32_16x16x32_f16 v[110:113], v[54:57], v[198:201], v[110:113]
	v_mfma_f32_16x16x32_f16 v[106:109], v[66:69], v[198:201], v[106:109]
	v_mfma_f32_16x16x32_f16 v[158:161], v[58:61], v[166:169], v[158:161]
	v_mfma_f32_16x16x32_f16 v[154:157], v[70:73], v[166:169], v[154:157]
	v_mfma_f32_16x16x32_f16 v[142:145], v[58:61], v[174:177], v[142:145]
	v_mfma_f32_16x16x32_f16 v[138:141], v[70:73], v[174:177], v[138:141]
	v_mfma_f32_16x16x32_f16 v[126:129], v[58:61], v[194:197], v[126:129]
	v_mfma_f32_16x16x32_f16 v[122:125], v[70:73], v[194:197], v[122:125]
	v_mfma_f32_16x16x32_f16 v[110:113], v[58:61], v[202:205], v[110:113]
	v_mfma_f32_16x16x32_f16 v[106:109], v[70:73], v[202:205], v[106:109]
	s_setprio 0
	s_setprio 1
	v_mfma_f32_16x16x32_f16 v[150:153], v[74:77], v[162:165], v[150:153]
	v_mfma_f32_16x16x32_f16 v[146:149], v[82:85], v[162:165], v[146:149]
	v_mfma_f32_16x16x32_f16 v[134:137], v[74:77], v[170:173], v[134:137]
	v_mfma_f32_16x16x32_f16 v[130:133], v[82:85], v[170:173], v[130:133]
	v_mfma_f32_16x16x32_f16 v[118:121], v[74:77], v[190:193], v[118:121]
	v_mfma_f32_16x16x32_f16 v[114:117], v[82:85], v[190:193], v[114:117]
	v_mfma_f32_16x16x32_f16 v[102:105], v[74:77], v[198:201], v[102:105]
	v_mfma_f32_16x16x32_f16 v[98:101], v[82:85], v[198:201], v[98:101]
	v_mfma_f32_16x16x32_f16 v[150:153], v[78:81], v[166:169], v[150:153]
	v_mfma_f32_16x16x32_f16 v[146:149], v[86:89], v[166:169], v[146:149]
	v_mfma_f32_16x16x32_f16 v[134:137], v[78:81], v[174:177], v[134:137]
	v_mfma_f32_16x16x32_f16 v[130:133], v[86:89], v[174:177], v[130:133]
	v_mfma_f32_16x16x32_f16 v[118:121], v[78:81], v[194:197], v[118:121]
	v_mfma_f32_16x16x32_f16 v[114:117], v[86:89], v[194:197], v[114:117]
	v_mfma_f32_16x16x32_f16 v[102:105], v[78:81], v[202:205], v[102:105]
	v_mfma_f32_16x16x32_f16 v[98:101], v[86:89], v[202:205], v[98:101]
	s_setprio 0
	s_barrier
; #define PG8_STAGE(bufoff, gbase, voff) do { _Pragma("unroll") for (int _i = 0; _i < 2; ++_i) \
;         __builtin_amdgcn_global_load_lds((const unsigned*)((const char*)(gbase) + (voff)[_i]), (PG8_LAS unsigned*)(lds + (bufoff) + ldsw + _i * 8192), 16, 0, 0); } while (0)
; #define PG8_LDA(dst, b, h) do { _Pragma("unroll") for (int m = 0; m < 4; ++m) _Pragma("unroll") for (int k = 0; k < 2; ++k) dst[m][k] = *(const PG8_LAS bf16x8*)(lds + PG8_SA(b, h) + aoff + m * 2048 + k * 1024); } while (0)
; #define PG8_MMA(ai, bj, At, Bt) do { __builtin_amdgcn_s_setprio(1); _Pragma("unroll") for (int m = 0; m < 4; ++m) _Pragma("unroll") for (int n = 0; n < 2; ++n) _Pragma("unroll") for (int k = 0; k < 2; ++k) \
;         acc[ai][bj][m][n] = mma16<Epi::F16>(Bt[n][k], At[m][k], acc[ai][bj][m][n]); __builtin_amdgcn_s_setprio(0); } while (0)
; #define PG8_WAIT_V(n) asm volatile("s_waitcnt vmcnt(" #n ")" ::: "memory")
; #define PG8_WAIT_L(n) asm volatile("s_waitcnt lgkmcnt(" #n ")" ::: "memory")
; #define PG8_BAR __builtin_amdgcn_s_barrier()
; #define PG8_SCHED __builtin_amdgcn_sched_barrier(0)
; template <class Epi, class Sched, bool ALIGN_EPI = false, bool SP2 = false>
; __device__ __forceinline__ void gemm_phase(PG8_LAS unsigned char* lds, const Gemm g, const Sched& S, const Epi& E, const int wave_in) {
;     ...
;         for (int t = 0; t < nt; t += 2) {
;             const bool last = (t == nt - 2);
;             const char* a1 = cA + (size_t)(t + 1) * kstep;
;             const char* a2 = last ? nA : cA + (size_t)(t + 2) * kstep; const char* b2 = last ? nB : cB + (size_t)(t + 2) * kstep;
;             const char* a3 = a2 + kstep; const char* b3 = b2 + kstep;
;             if (last && has_next) S.a_ready(nxt);
;     ...
;             PG8_LDA(At, 1, 1); PG8_STAGE(PG8_SB(1, 0), b3, voffB); PG8_STAGE(PG8_SB(1, 1), b3 + hstep, voffB); PG8_STAGE(PG8_SA(1, 0), a3, voffA);
;             PG8_WAIT_V(8); PG8_WAIT_L(0); PG8_BAR; PG8_MMA(1, 0, At, B0); PG8_MMA(1, 1, At, B1); PG8_BAR; PG8_SCHED;
	s_add_i32 s13, s73, s82
	v_lshl_add_u64 v[212:213], v[212:213], 0, s[78:79]
	s_mov_b32 m0, s13
	ds_read_b128 v[162:165], v229 offset:49152
	ds_read_b128 v[166:169], v229 offset:50176
	ds_read_b128 v[170:173], v229 offset:51200
	ds_read_b128 v[174:177], v229 offset:52224
	ds_read_b128 v[190:193], v229 offset:53248
	ds_read_b128 v[194:197], v229 offset:54272
	ds_read_b128 v[198:201], v229 offset:55296
	ds_read_b128 v[202:205], v229 offset:56320
	global_load_lds_dwordx4 v[212:213], off
	s_add_i32 m0, s13, 0x2000
	s_add_u32 s36, s36, 0x40080
	v_lshl_add_u64 v[212:213], v[214:215], 0, s[78:79]
	s_addc_u32 s37, s37, 0
	s_add_i32 s13, s74, s82
	global_load_lds_dwordx4 v[212:213], off
	v_lshl_add_u64 v[212:213], s[36:37], 0, v[0:1]
	s_mov_b32 m0, s13
	s_nop 0
	global_load_lds_dwordx4 v[212:213], off
	v_lshl_add_u64 v[212:213], s[36:37], 0, v[182:183]
	s_add_i32 m0, s13, 0x2000
	s_nop 0
	global_load_lds_dwordx4 v[212:213], off
	v_lshl_add_u64 v[212:213], v[216:217], 0, s[78:79]
	s_mov_b32 m0, s1
	s_nop 0
	global_load_lds_dwordx4 v[212:213], off
	v_lshl_add_u64 v[212:213], v[218:219], 0, s[78:79]
	s_mov_b32 m0, s76
	s_nop 0
	global_load_lds_dwordx4 v[212:213], off
	s_waitcnt vmcnt(8)
	s_waitcnt lgkmcnt(0)
	s_barrier
	s_setprio 1
	s_waitcnt lgkmcnt(0)
	v_mfma_f32_16x16x32_f16 v[94:97], v[54:57], v[162:165], v[94:97]
	v_mfma_f32_16x16x32_f16 v[90:93], v[66:69], v[162:165], v[90:93]
	v_mfma_f32_16x16x32_f16 v[62:65], v[54:57], v[170:173], v[62:65]
	v_mfma_f32_16x16x32_f16 v[50:53], v[66:69], v[170:173], v[50:53]
	v_mfma_f32_16x16x32_f16 v[30:33], v[54:57], v[190:193], v[30:33]
	v_mfma_f32_16x16x32_f16 v[26:29], v[66:69], v[190:193], v[26:29]
	v_mfma_f32_16x16x32_f16 v[14:17], v[54:57], v[198:201], v[14:17]
	v_mfma_f32_16x16x32_f16 v[10:13], v[66:69], v[198:201], v[10:13]
	v_mfma_f32_16x16x32_f16 v[94:97], v[58:61], v[166:169], v[94:97]
	v_mfma_f32_16x16x32_f16 v[90:93], v[70:73], v[166:169], v[90:93]
	v_mfma_f32_16x16x32_f16 v[62:65], v[58:61], v[174:177], v[62:65]
	v_mfma_f32_16x16x32_f16 v[50:53], v[70:73], v[174:177], v[50:53]
	v_mfma_f32_16x16x32_f16 v[30:33], v[58:61], v[194:197], v[30:33]
	v_mfma_f32_16x16x32_f16 v[26:29], v[70:73], v[194:197], v[26:29]
	v_mfma_f32_16x16x32_f16 v[14:17], v[58:61], v[202:205], v[14:17]
	v_mfma_f32_16x16x32_f16 v[10:13], v[70:73], v[202:205], v[10:13]
	s_setprio 0
	s_setprio 1
	v_mfma_f32_16x16x32_f16 v[42:45], v[74:77], v[162:165], v[42:45]
	v_mfma_f32_16x16x32_f16 v[70:73], v[78:81], v[166:169], v[42:45]
	v_mfma_f32_16x16x32_f16 v[42:45], v[82:85], v[162:165], v[46:49]
	v_mfma_f32_16x16x32_f16 v[38:41], v[74:77], v[170:173], v[38:41]
	v_mfma_f32_16x16x32_f16 v[34:37], v[82:85], v[170:173], v[34:37]
	v_mfma_f32_16x16x32_f16 v[22:25], v[74:77], v[190:193], v[22:25]
	v_mfma_f32_16x16x32_f16 v[18:21], v[82:85], v[190:193], v[18:21]
	v_mfma_f32_16x16x32_f16 v[6:9], v[74:77], v[198:201], v[6:9]
	v_mfma_f32_16x16x32_f16 v[2:5], v[82:85], v[198:201], v[2:5]
	v_mfma_f32_16x16x32_f16 v[66:69], v[86:89], v[166:169], v[42:45]
	v_mfma_f32_16x16x32_f16 v[38:41], v[78:81], v[174:177], v[38:41]
	v_mfma_f32_16x16x32_f16 v[34:37], v[86:89], v[174:177], v[34:37]
	v_mfma_f32_16x16x32_f16 v[22:25], v[78:81], v[194:197], v[22:25]
	v_mfma_f32_16x16x32_f16 v[18:21], v[86:89], v[194:197], v[18:21]
	v_mfma_f32_16x16x32_f16 v[6:9], v[78:81], v[202:205], v[6:9]
	v_mfma_f32_16x16x32_f16 v[2:5], v[86:89], v[202:205], v[2:5]
	s_setprio 0
	s_add_i32 s12, s12, 2
	s_add_u32 s38, s38, 0x100
	s_addc_u32 s39, s39, 0
	s_add_u32 s45, s45, 0x100
	s_addc_u32 s59, s59, 0
	s_cmp_gt_u32 s12, 13
	s_barrier
	s_cbranch_scc0 .LBB0_594
	s_and_b64 vcc, exec, s[56:57]
	s_cbranch_vccz .LBB0_597
	s_barrier

; #define PG8_STAGE(bufoff, gbase, voff) do { _Pragma("unroll") for (int _i = 0; _i < 2; ++_i) \
;         __builtin_amdgcn_global_load_lds((const unsigned*)((const char*)(gbase) + (voff)[_i]), (PG8_LAS unsigned*)(lds + (bufoff) + ldsw + _i * 8192), 16, 0, 0); } while (0)
; #define PG8_LDA(dst, b, h) do { _Pragma("unroll") for (int m = 0; m < 4; ++m) _Pragma("unroll") for (int k = 0; k < 2; ++k) dst[m][k] = *(const PG8_LAS bf16x8*)(lds + PG8_SA(b, h) + aoff + m * 2048 + k * 1024); } while (0)
; #define PG8_LDB(dst, b, h) do { _Pragma("unroll") for (int n = 0; n < 2; ++n) _Pragma("unroll") for (int k = 0; k < 2; ++k) dst[n][k] = *(const PG8_LAS bf16x8*)(lds + PG8_SB(b, h) + boff + n * 2048 + k * 1024); } while (0)
; #define PG8_MMA(ai, bj, At, Bt) do { __builtin_amdgcn_s_setprio(1); _Pragma("unroll") for (int m = 0; m < 4; ++m) _Pragma("unroll") for (int n = 0; n < 2; ++n) _Pragma("unroll") for (int k = 0; k < 2; ++k) \
;         acc[ai][bj][m][n] = mma16<Epi::F16>(Bt[n][k], At[m][k], acc[ai][bj][m][n]); __builtin_amdgcn_s_setprio(0); } while (0)
; #define PG8_WAIT_V(n) asm volatile("s_waitcnt vmcnt(" #n ")" ::: "memory")
; #define PG8_WAIT_L(n) asm volatile("s_waitcnt lgkmcnt(" #n ")" ::: "memory")
; template <class Epi, class Sched, bool ALIGN_EPI = false, bool SP2 = false>
; __device__ __forceinline__ void gemm_phase(PG8_LAS unsigned char* lds, const Gemm g, const Sched& S, const Epi& E, const int wave_in) {
;     ...
;         for (int t = 0; t < nt; t += 2) {
;             const bool last = (t == nt - 2);
;             const char* a1 = cA + (size_t)(t + 1) * kstep;
;             const char* a2 = last ? nA : cA + (size_t)(t + 2) * kstep; const char* b2 = last ? nB : cB + (size_t)(t + 2) * kstep;
;             const char* a3 = a2 + kstep; const char* b3 = b2 + kstep;
;             if (last && has_next) S.a_ready(nxt);
;             if constexpr (SP2) {
;             PG8_LDB(B0, 0, 0); PG8_LDB(B1, 0, 1); PG8_SCHED; PG8_LDA(At, 0, 0); PG8_STAGE(PG8_SA(1, 1), a1 + hstep, voffA);
;             PG8_WAIT_V(8); PG8_WAIT_L(0); PG8_BAR; PG8_MMA(0, 0, At, B0); PG8_MMA(0, 1, At, B1); PG8_BAR; PG8_SCHED;
;             PG8_LDA(At, 0, 1); PG8_STAGE(PG8_SB(0, 0), b2, voffB); PG8_STAGE(PG8_SB(0, 1), b2 + hstep, voffB); PG8_STAGE(PG8_SA(0, 0), a2, voffA);
;             PG8_WAIT_V(8); PG8_WAIT_L(0); PG8_BAR; PG8_MMA(1, 0, At, B0); PG8_MMA(1, 1, At, B1); PG8_BAR; PG8_SCHED;
.LBB0_859:
	v_add_u32_e32 v62, s28, v211
	v_add_u32_e32 v78, s72, v211
	ds_read_b128 v[42:45], v62
	ds_read_b128 v[46:49], v62 offset:1024
	ds_read_b128 v[54:57], v62 offset:2048
	ds_read_b128 v[62:65], v62 offset:3072
	ds_read_b128 v[66:69], v78
	ds_read_b128 v[70:73], v78 offset:1024
	ds_read_b128 v[74:77], v78 offset:2048
	ds_read_b128 v[78:81], v78 offset:3072
	s_add_u32 s14, s90, 0xfffc0080
	s_addc_u32 s15, s91, -1
	s_cmp_eq_u32 s13, 12
	s_cselect_b32 vcc_hi, s10, s15
	s_cselect_b32 vcc_lo, s11, s14
	s_cselect_b32 s37, s57, s12
	s_cselect_b32 s36, s59, s83
	v_lshl_add_u64 v[178:179], s[90:91], 0, v[220:221]
	s_add_i32 m0, s5, 0xc000
	ds_read_b128 v[98:101], v213
	ds_read_b128 v[102:105], v213 offset:1024
	ds_read_b128 v[106:109], v213 offset:2048
	ds_read_b128 v[118:121], v213 offset:3072
	ds_read_b128 v[130:133], v213 offset:4096
	ds_read_b128 v[138:141], v213 offset:5120
	ds_read_b128 v[146:149], v213 offset:6144
	ds_read_b128 v[158:161], v213 offset:7168
	global_load_lds_dwordx4 v[178:179], off
	v_lshl_add_u64 v[178:179], s[90:91], 0, v[222:223]
	s_add_i32 m0, s5, 0xe000
	s_nop 0
	global_load_lds_dwordx4 v[178:179], off
	s_waitcnt vmcnt(8)
	s_waitcnt lgkmcnt(0)
	s_barrier
	s_setprio 1
	s_waitcnt lgkmcnt(0)
	v_mfma_f32_16x16x32_bf16 v[190:193], v[54:57], v[98:101], v[190:193]
	v_mfma_f32_16x16x32_bf16 v[174:177], v[42:45], v[106:109], v[174:177]
	v_mfma_f32_16x16x32_bf16 v[170:173], v[54:57], v[106:109], v[170:173]
	v_mfma_f32_16x16x32_bf16 v[154:157], v[42:45], v[130:133], v[154:157]
	v_mfma_f32_16x16x32_bf16 v[150:153], v[54:57], v[130:133], v[150:153]
	v_mfma_f32_16x16x32_bf16 v[126:129], v[42:45], v[146:149], v[126:129]
	v_mfma_f32_16x16x32_bf16 v[122:125], v[54:57], v[146:149], v[122:125]
	v_mfma_f32_16x16x32_bf16 v[178:181], v[42:45], v[98:101], v[194:197]
	v_mfma_f32_16x16x32_bf16 v[190:193], v[62:65], v[102:105], v[190:193]
	v_mfma_f32_16x16x32_bf16 v[174:177], v[46:49], v[118:121], v[174:177]
	v_mfma_f32_16x16x32_bf16 v[170:173], v[62:65], v[118:121], v[170:173]
	v_mfma_f32_16x16x32_bf16 v[154:157], v[46:49], v[138:141], v[154:157]
	v_mfma_f32_16x16x32_bf16 v[150:153], v[62:65], v[138:141], v[150:153]
	v_mfma_f32_16x16x32_bf16 v[126:129], v[46:49], v[158:161], v[126:129]
	v_mfma_f32_16x16x32_bf16 v[122:125], v[62:65], v[158:161], v[122:125]
	v_mfma_f32_16x16x32_bf16 v[178:181], v[46:49], v[102:105], v[178:181]
	s_setprio 0
	s_setprio 1
	v_mfma_f32_16x16x32_bf16 v[186:189], v[66:69], v[98:101], v[186:189]
	v_mfma_f32_16x16x32_bf16 v[98:101], v[74:77], v[98:101], v[182:185]
	v_mfma_f32_16x16x32_bf16 v[186:189], v[70:73], v[102:105], v[186:189]
	v_mfma_f32_16x16x32_bf16 v[98:101], v[78:81], v[102:105], v[98:101]
	v_mfma_f32_16x16x32_bf16 v[102:105], v[66:69], v[106:109], v[166:169]
	v_mfma_f32_16x16x32_bf16 v[106:109], v[74:77], v[106:109], v[162:165]
	v_mfma_f32_16x16x32_bf16 v[114:117], v[66:69], v[146:149], v[114:117]
	v_mfma_f32_16x16x32_bf16 v[110:113], v[74:77], v[146:149], v[110:113]
	v_mfma_f32_16x16x32_bf16 v[102:105], v[70:73], v[118:121], v[102:105]
	v_mfma_f32_16x16x32_bf16 v[106:109], v[78:81], v[118:121], v[106:109]
	v_mfma_f32_16x16x32_bf16 v[118:121], v[66:69], v[130:133], v[142:145]
	v_mfma_f32_16x16x32_bf16 v[130:133], v[74:77], v[130:133], v[134:137]
	v_mfma_f32_16x16x32_bf16 v[114:117], v[70:73], v[158:161], v[114:117]
	v_mfma_f32_16x16x32_bf16 v[110:113], v[78:81], v[158:161], v[110:113]
	v_mfma_f32_16x16x32_bf16 v[118:121], v[70:73], v[138:141], v[118:121]
	v_mfma_f32_16x16x32_bf16 v[130:133], v[78:81], v[138:141], v[130:133]
	s_setprio 0
	s_barrier
	s_add_i32 s14, s28, s4
	v_lshl_add_u64 v[228:229], s[36:37], 0, v[0:1]
	s_mov_b32 m0, s14
	ds_read_b128 v[134:137], v213 offset:16384
	ds_read_b128 v[138:141], v213 offset:17408
	ds_read_b128 v[142:145], v213 offset:18432
	ds_read_b128 v[146:149], v213 offset:19456
	ds_read_b128 v[158:161], v213 offset:20480
	ds_read_b128 v[162:165], v213 offset:21504
	ds_read_b128 v[166:169], v213 offset:22528
	ds_read_b128 v[182:185], v213 offset:23552
	global_load_lds_dwordx4 v[228:229], off
	s_add_i32 m0, s14, 0x2000
	s_add_u32 s14, s36, 0x40000
	v_lshl_add_u64 v[230:231], s[36:37], 0, v[218:219]
	s_addc_u32 s15, s37, 0
	s_add_i32 s16, s72, s4
	global_load_lds_dwordx4 v[230:231], off
	v_lshl_add_u64 v[194:195], s[14:15], 0, v[0:1]
	s_mov_b32 m0, s16
	v_lshl_add_u64 v[232:233], vcc, 0, v[214:215]
	global_load_lds_dwordx4 v[194:195], off
	v_lshl_add_u64 v[194:195], s[14:15], 0, v[218:219]
	s_add_i32 m0, s16, 0x2000
	v_lshl_add_u64 v[234:235], vcc, 0, v[216:217]
	global_load_lds_dwordx4 v[194:195], off
	s_mov_b32 m0, s5
	s_nop 0
	global_load_lds_dwordx4 v[232:233], off
	s_mov_b32 m0, s49
	s_nop 0
	global_load_lds_dwordx4 v[234:235], off
	s_waitcnt vmcnt(8)
	s_waitcnt lgkmcnt(0)
	s_barrier
; #define PG8_STAGE(bufoff, gbase, voff) do { _Pragma("unroll") for (int _i = 0; _i < 2; ++_i) \
;         __builtin_amdgcn_global_load_lds((const unsigned*)((const char*)(gbase) + (voff)[_i]), (PG8_LAS unsigned*)(lds + (bufoff) + ldsw + _i * 8192), 16, 0, 0); } while (0)
; #define PG8_LDA(dst, b, h) do { _Pragma("unroll") for (int m = 0; m < 4; ++m) _Pragma("unroll") for (int k = 0; k < 2; ++k) dst[m][k] = *(const PG8_LAS bf16x8*)(lds + PG8_SA(b, h) + aoff + m * 2048 + k * 1024); } while (0)
; #define PG8_LDB(dst, b, h) do { _Pragma("unroll") for (int n = 0; n < 2; ++n) _Pragma("unroll") for (int k = 0; k < 2; ++k) dst[n][k] = *(const PG8_LAS bf16x8*)(lds + PG8_SB(b, h) + boff + n * 2048 + k * 1024); } while (0)
; #define PG8_MMA(ai, bj, At, Bt) do { __builtin_amdgcn_s_setprio(1); _Pragma("unroll") for (int m = 0; m < 4; ++m) _Pragma("unroll") for (int n = 0; n < 2; ++n) _Pragma("unroll") for (int k = 0; k < 2; ++k) \
;         acc[ai][bj][m][n] = mma16<Epi::F16>(Bt[n][k], At[m][k], acc[ai][bj][m][n]); __builtin_amdgcn_s_setprio(0); } while (0)
; #define PG8_WAIT_V(n) asm volatile("s_waitcnt vmcnt(" #n ")" ::: "memory")
; #define PG8_WAIT_L(n) asm volatile("s_waitcnt lgkmcnt(" #n ")" ::: "memory")
; #define PG8_BAR __builtin_amdgcn_s_barrier()
; #define PG8_SCHED __builtin_amdgcn_sched_barrier(0)
; template <class Epi, class Sched, bool ALIGN_EPI = false, bool SP2 = false>
; __device__ __forceinline__ void gemm_phase(PG8_LAS unsigned char* lds, const Gemm g, const Sched& S, const Epi& E, const int wave_in) {
;     ...
;             PG8_WAIT_V(8); PG8_WAIT_L(0); PG8_BAR; PG8_MMA(1, 0, At, B0); PG8_MMA(1, 1, At, B1); PG8_BAR; PG8_SCHED;
;             PG8_LDB(B0, 1, 0); PG8_LDB(B1, 1, 1); PG8_SCHED; PG8_LDA(At, 1, 0); PG8_STAGE(PG8_SA(0, 1), a2 + hstep, voffA);
;             PG8_WAIT_V(8); PG8_WAIT_L(0); PG8_BAR; PG8_MMA(0, 0, At, B0); PG8_MMA(0, 1, At, B1); PG8_BAR; PG8_SCHED;
	s_setprio 1
	s_waitcnt lgkmcnt(0)
	v_mfma_f32_16x16x32_bf16 v[94:97], v[42:45], v[134:137], v[94:97]
	v_mfma_f32_16x16x32_bf16 v[90:93], v[54:57], v[134:137], v[90:93]
	v_mfma_f32_16x16x32_bf16 v[58:61], v[42:45], v[142:145], v[58:61]
	v_mfma_f32_16x16x32_bf16 v[50:53], v[54:57], v[142:145], v[50:53]
	v_mfma_f32_16x16x32_bf16 v[30:33], v[42:45], v[158:161], v[30:33]
	v_mfma_f32_16x16x32_bf16 v[26:29], v[54:57], v[158:161], v[26:29]
	v_mfma_f32_16x16x32_bf16 v[14:17], v[42:45], v[166:169], v[14:17]
	v_mfma_f32_16x16x32_bf16 v[10:13], v[54:57], v[166:169], v[10:13]
	v_mfma_f32_16x16x32_bf16 v[94:97], v[46:49], v[138:141], v[94:97]
	v_mfma_f32_16x16x32_bf16 v[90:93], v[62:65], v[138:141], v[90:93]
	v_mfma_f32_16x16x32_bf16 v[58:61], v[46:49], v[146:149], v[58:61]
	v_mfma_f32_16x16x32_bf16 v[50:53], v[62:65], v[146:149], v[50:53]
	v_mfma_f32_16x16x32_bf16 v[30:33], v[46:49], v[162:165], v[30:33]
	v_mfma_f32_16x16x32_bf16 v[26:29], v[62:65], v[162:165], v[26:29]
	v_mfma_f32_16x16x32_bf16 v[14:17], v[46:49], v[182:185], v[14:17]
	v_mfma_f32_16x16x32_bf16 v[10:13], v[62:65], v[182:185], v[10:13]
	s_setprio 0
	s_setprio 1
	v_mfma_f32_16x16x32_bf16 v[38:41], v[66:69], v[142:145], v[38:41]
	v_mfma_f32_16x16x32_bf16 v[34:37], v[74:77], v[142:145], v[34:37]
	v_mfma_f32_16x16x32_bf16 v[22:25], v[66:69], v[158:161], v[22:25]
	v_mfma_f32_16x16x32_bf16 v[18:21], v[74:77], v[158:161], v[18:21]
	v_mfma_f32_16x16x32_bf16 v[6:9], v[66:69], v[166:169], v[6:9]
	v_mfma_f32_16x16x32_bf16 v[2:5], v[74:77], v[166:169], v[2:5]
	v_mfma_f32_16x16x32_bf16 v[42:45], v[66:69], v[134:137], v[86:89]
	v_mfma_f32_16x16x32_bf16 v[46:49], v[74:77], v[134:137], v[82:85]
	v_mfma_f32_16x16x32_bf16 v[38:41], v[70:73], v[146:149], v[38:41]
	v_mfma_f32_16x16x32_bf16 v[34:37], v[78:81], v[146:149], v[34:37]
	v_mfma_f32_16x16x32_bf16 v[22:25], v[70:73], v[162:165], v[22:25]
	v_mfma_f32_16x16x32_bf16 v[18:21], v[78:81], v[162:165], v[18:21]
	v_mfma_f32_16x16x32_bf16 v[6:9], v[70:73], v[182:185], v[6:9]
	v_mfma_f32_16x16x32_bf16 v[2:5], v[78:81], v[182:185], v[2:5]
	v_mfma_f32_16x16x32_bf16 v[42:45], v[70:73], v[138:141], v[42:45]
	v_mfma_f32_16x16x32_bf16 v[46:49], v[78:81], v[138:141], v[46:49]
	s_setprio 0
	s_barrier
	v_add_u32_e32 v70, s73, v211
	v_add_u32_e32 v82, s74, v211
	ds_read_b128 v[54:57], v70
	ds_read_b128 v[62:65], v70 offset:1024
	ds_read_b128 v[66:69], v70 offset:2048
	ds_read_b128 v[70:73], v70 offset:3072
	ds_read_b128 v[74:77], v82
	ds_read_b128 v[78:81], v82 offset:1024
	ds_read_b128 v[138:141], v82 offset:2048
	ds_read_b128 v[146:149], v82 offset:3072
	s_add_u32 s14, vcc_lo, 0x40000
	s_addc_u32 s15, vcc_hi, 0
	s_mov_b32 m0, s71
	v_lshl_add_u64 v[162:163], s[14:15], 0, v[214:215]
	ds_read_b128 v[82:85], v213 offset:32768
	ds_read_b128 v[86:89], v213 offset:33792
	ds_read_b128 v[134:137], v213 offset:34816
	ds_read_b128 v[142:145], v213 offset:35840
	ds_read_b128 v[158:161], v213 offset:36864
	ds_read_b128 v[198:201], v213 offset:37888
	ds_read_b128 v[202:205], v213 offset:38912
	ds_read_b128 v[224:227], v213 offset:39936
	global_load_lds_dwordx4 v[162:163], off
	v_lshl_add_u64 v[162:163], s[14:15], 0, v[216:217]
	s_mov_b32 m0, s82
	s_nop 0
	global_load_lds_dwordx4 v[162:163], off
	s_waitcnt vmcnt(8)
	s_waitcnt lgkmcnt(0)
	s_barrier
	s_setprio 1
	s_waitcnt lgkmcnt(0)
	v_mfma_f32_16x16x32_bf16 v[162:165], v[54:57], v[82:85], v[178:181]
	v_mfma_f32_16x16x32_bf16 v[194:197], v[62:65], v[86:89], v[162:165]
	v_mfma_f32_16x16x32_bf16 v[162:165], v[66:69], v[82:85], v[190:193]
	v_mfma_f32_16x16x32_bf16 v[190:193], v[70:73], v[86:89], v[162:165]
	v_mfma_f32_16x16x32_bf16 v[162:165], v[54:57], v[134:137], v[174:177]
	v_mfma_f32_16x16x32_bf16 v[174:177], v[62:65], v[142:145], v[162:165]
	v_mfma_f32_16x16x32_bf16 v[162:165], v[66:69], v[134:137], v[170:173]
	v_mfma_f32_16x16x32_bf16 v[154:157], v[54:57], v[158:161], v[154:157]
	v_mfma_f32_16x16x32_bf16 v[150:153], v[66:69], v[158:161], v[150:153]
	v_mfma_f32_16x16x32_bf16 v[126:129], v[54:57], v[202:205], v[126:129]
	v_mfma_f32_16x16x32_bf16 v[122:125], v[66:69], v[202:205], v[122:125]
	v_mfma_f32_16x16x32_bf16 v[170:173], v[70:73], v[142:145], v[162:165]
	v_mfma_f32_16x16x32_bf16 v[154:157], v[62:65], v[198:201], v[154:157]
	v_mfma_f32_16x16x32_bf16 v[150:153], v[70:73], v[198:201], v[150:153]
	v_mfma_f32_16x16x32_bf16 v[126:129], v[62:65], v[224:227], v[126:129]
	v_mfma_f32_16x16x32_bf16 v[122:125], v[70:73], v[224:227], v[122:125]
	s_setprio 0
	s_setprio 1
	v_mfma_f32_16x16x32_bf16 v[162:165], v[74:77], v[82:85], v[186:189]
	v_mfma_f32_16x16x32_bf16 v[82:85], v[138:141], v[82:85], v[98:101]
	v_mfma_f32_16x16x32_bf16 v[182:185], v[146:149], v[86:89], v[82:85]
	v_mfma_f32_16x16x32_bf16 v[82:85], v[74:77], v[134:137], v[102:105]
	v_mfma_f32_16x16x32_bf16 v[166:169], v[78:81], v[142:145], v[82:85]
	v_mfma_f32_16x16x32_bf16 v[82:85], v[138:141], v[134:137], v[106:109]
	v_mfma_f32_16x16x32_bf16 v[186:189], v[78:81], v[86:89], v[162:165]
	v_mfma_f32_16x16x32_bf16 v[162:165], v[146:149], v[142:145], v[82:85]
	v_mfma_f32_16x16x32_bf16 v[82:85], v[74:77], v[158:161], v[118:121]
	v_mfma_f32_16x16x32_bf16 v[142:145], v[78:81], v[198:201], v[82:85]
	v_mfma_f32_16x16x32_bf16 v[82:85], v[138:141], v[158:161], v[130:133]
	v_mfma_f32_16x16x32_bf16 v[134:137], v[146:149], v[198:201], v[82:85]
	v_mfma_f32_16x16x32_bf16 v[82:85], v[74:77], v[202:205], v[114:117]
	v_mfma_f32_16x16x32_bf16 v[114:117], v[78:81], v[224:227], v[82:85]
	v_mfma_f32_16x16x32_bf16 v[82:85], v[138:141], v[202:205], v[110:113]
	v_mfma_f32_16x16x32_bf16 v[110:113], v[146:149], v[224:227], v[82:85]
	s_setprio 0
	s_barrier
; #define PG8_STAGE(bufoff, gbase, voff) do { _Pragma("unroll") for (int _i = 0; _i < 2; ++_i) \
;         __builtin_amdgcn_global_load_lds((const unsigned*)((const char*)(gbase) + (voff)[_i]), (PG8_LAS unsigned*)(lds + (bufoff) + ldsw + _i * 8192), 16, 0, 0); } while (0)
; #define PG8_LDA(dst, b, h) do { _Pragma("unroll") for (int m = 0; m < 4; ++m) _Pragma("unroll") for (int k = 0; k < 2; ++k) dst[m][k] = *(const PG8_LAS bf16x8*)(lds + PG8_SA(b, h) + aoff + m * 2048 + k * 1024); } while (0)
; #define PG8_MMA(ai, bj, At, Bt) do { __builtin_amdgcn_s_setprio(1); _Pragma("unroll") for (int m = 0; m < 4; ++m) _Pragma("unroll") for (int n = 0; n < 2; ++n) _Pragma("unroll") for (int k = 0; k < 2; ++k) \
;         acc[ai][bj][m][n] = mma16<Epi::F16>(Bt[n][k], At[m][k], acc[ai][bj][m][n]); __builtin_amdgcn_s_setprio(0); } while (0)
; #define PG8_WAIT_V(n) asm volatile("s_waitcnt vmcnt(" #n ")" ::: "memory")
; #define PG8_WAIT_L(n) asm volatile("s_waitcnt lgkmcnt(" #n ")" ::: "memory")
; #define PG8_BAR __builtin_amdgcn_s_barrier()
; #define PG8_SCHED __builtin_amdgcn_sched_barrier(0)
; template <class Epi, class Sched, bool ALIGN_EPI = false, bool SP2 = false>
; __device__ __forceinline__ void gemm_phase(PG8_LAS unsigned char* lds, const Gemm g, const Sched& S, const Epi& E, const int wave_in) {
;     ...
;         for (int t = 0; t < nt; t += 2) {
;             const bool last = (t == nt - 2);
;             const char* a1 = cA + (size_t)(t + 1) * kstep;
;             const char* a2 = last ? nA : cA + (size_t)(t + 2) * kstep; const char* b2 = last ? nB : cB + (size_t)(t + 2) * kstep;
;             const char* a3 = a2 + kstep; const char* b3 = b2 + kstep;
;             if (last && has_next) S.a_ready(nxt);
;     ...
;             PG8_LDA(At, 1, 1); PG8_STAGE(PG8_SB(1, 0), b3, voffB); PG8_STAGE(PG8_SB(1, 1), b3 + hstep, voffB); PG8_STAGE(PG8_SA(1, 0), a3, voffA);
;             PG8_WAIT_V(8); PG8_WAIT_L(0); PG8_BAR; PG8_MMA(1, 0, At, B0); PG8_MMA(1, 1, At, B1); PG8_BAR; PG8_SCHED;
	s_add_i32 s14, s73, s4
	v_lshl_add_u64 v[86:87], v[228:229], 0, s[78:79]
	s_mov_b32 m0, s14
	s_nop 1
	ds_read_b128 v[82:85], v213 offset:49152
	ds_read_b128 v[98:101], v213 offset:50176
	ds_read_b128 v[102:105], v213 offset:51200
	ds_read_b128 v[106:109], v213 offset:52224
	ds_read_b128 v[118:121], v213 offset:53248
	ds_read_b128 v[130:133], v213 offset:54272
	ds_read_b128 v[158:161], v213 offset:55296
	ds_read_b128 v[178:181], v213 offset:56320
	global_load_lds_dwordx4 v[86:87], off
	s_add_i32 m0, s14, 0x2000
	s_add_u32 s14, s36, 0x40080
	v_lshl_add_u64 v[86:87], v[230:231], 0, s[78:79]
	s_addc_u32 s15, s37, 0
	s_add_i32 s16, s74, s4
	global_load_lds_dwordx4 v[86:87], off
	v_lshl_add_u64 v[86:87], s[14:15], 0, v[0:1]
	s_mov_b32 m0, s16
	s_nop 0
	global_load_lds_dwordx4 v[86:87], off
	v_lshl_add_u64 v[86:87], s[14:15], 0, v[218:219]
	s_add_i32 m0, s16, 0x2000
	s_nop 0
	global_load_lds_dwordx4 v[86:87], off
	v_lshl_add_u64 v[86:87], v[232:233], 0, s[78:79]
	s_mov_b32 m0, s6
	s_nop 0
	global_load_lds_dwordx4 v[86:87], off
	v_lshl_add_u64 v[86:87], v[234:235], 0, s[78:79]
	s_mov_b32 m0, s7
	s_nop 0
	global_load_lds_dwordx4 v[86:87], off
	s_waitcnt vmcnt(8)
	s_waitcnt lgkmcnt(0)
	s_barrier
	s_setprio 1
	s_waitcnt lgkmcnt(0)
	v_mfma_f32_16x16x32_bf16 v[86:89], v[54:57], v[82:85], v[94:97]
	v_mfma_f32_16x16x32_bf16 v[94:97], v[62:65], v[98:101], v[86:89]
	v_mfma_f32_16x16x32_bf16 v[86:89], v[66:69], v[82:85], v[90:93]
	v_mfma_f32_16x16x32_bf16 v[58:61], v[54:57], v[102:105], v[58:61]
	v_mfma_f32_16x16x32_bf16 v[50:53], v[66:69], v[102:105], v[50:53]
	v_mfma_f32_16x16x32_bf16 v[30:33], v[54:57], v[118:121], v[30:33]
	v_mfma_f32_16x16x32_bf16 v[26:29], v[66:69], v[118:121], v[26:29]
	v_mfma_f32_16x16x32_bf16 v[14:17], v[54:57], v[158:161], v[14:17]
	v_mfma_f32_16x16x32_bf16 v[10:13], v[66:69], v[158:161], v[10:13]
	v_mfma_f32_16x16x32_bf16 v[90:93], v[70:73], v[98:101], v[86:89]
	v_mfma_f32_16x16x32_bf16 v[58:61], v[62:65], v[106:109], v[58:61]
	v_mfma_f32_16x16x32_bf16 v[50:53], v[70:73], v[106:109], v[50:53]
	v_mfma_f32_16x16x32_bf16 v[30:33], v[62:65], v[130:133], v[30:33]
	v_mfma_f32_16x16x32_bf16 v[26:29], v[70:73], v[130:133], v[26:29]
	v_mfma_f32_16x16x32_bf16 v[14:17], v[62:65], v[178:181], v[14:17]
	v_mfma_f32_16x16x32_bf16 v[10:13], v[70:73], v[178:181], v[10:13]
	s_setprio 0
	s_setprio 1
	v_mfma_f32_16x16x32_bf16 v[42:45], v[74:77], v[82:85], v[42:45]
	v_mfma_f32_16x16x32_bf16 v[86:89], v[78:81], v[98:101], v[42:45]
	v_mfma_f32_16x16x32_bf16 v[42:45], v[138:141], v[82:85], v[46:49]
	v_mfma_f32_16x16x32_bf16 v[38:41], v[74:77], v[102:105], v[38:41]
	v_mfma_f32_16x16x32_bf16 v[34:37], v[138:141], v[102:105], v[34:37]
	v_mfma_f32_16x16x32_bf16 v[22:25], v[74:77], v[118:121], v[22:25]
	v_mfma_f32_16x16x32_bf16 v[18:21], v[138:141], v[118:121], v[18:21]
	v_mfma_f32_16x16x32_bf16 v[6:9], v[74:77], v[158:161], v[6:9]
	v_mfma_f32_16x16x32_bf16 v[2:5], v[138:141], v[158:161], v[2:5]
	v_mfma_f32_16x16x32_bf16 v[82:85], v[146:149], v[98:101], v[42:45]
	v_mfma_f32_16x16x32_bf16 v[38:41], v[78:81], v[106:109], v[38:41]
	v_mfma_f32_16x16x32_bf16 v[34:37], v[146:149], v[106:109], v[34:37]
	v_mfma_f32_16x16x32_bf16 v[22:25], v[78:81], v[130:133], v[22:25]
	v_mfma_f32_16x16x32_bf16 v[18:21], v[146:149], v[130:133], v[18:21]
	v_mfma_f32_16x16x32_bf16 v[6:9], v[78:81], v[178:181], v[6:9]
	v_mfma_f32_16x16x32_bf16 v[2:5], v[146:149], v[178:181], v[2:5]
	s_setprio 0
	s_add_i32 s13, s13, 2
	s_add_u32 s90, s90, 0x100
	s_addc_u32 s91, s91, 0
	s_add_u32 s83, s83, 0x100
	s_addc_u32 s12, s12, 0
	s_cmp_gt_u32 s13, 13
	s_barrier
	s_cbranch_scc0 .LBB0_859
	s_and_b64 vcc, exec, s[54:55]
	s_cbranch_vccz .LBB0_862
	s_barrier

; #define PG8_STAGE(bufoff, gbase, voff) do { _Pragma("unroll") for (int _i = 0; _i < 2; ++_i) \
;         __builtin_amdgcn_global_load_lds((const unsigned*)((const char*)(gbase) + (voff)[_i]), (PG8_LAS unsigned*)(lds + (bufoff) + ldsw + _i * 8192), 16, 0, 0); } while (0)
; #define PG8_LDA(dst, b, h) do { _Pragma("unroll") for (int m = 0; m < 4; ++m) _Pragma("unroll") for (int k = 0; k < 2; ++k) dst[m][k] = *(const PG8_LAS bf16x8*)(lds + PG8_SA(b, h) + aoff + m * 2048 + k * 1024); } while (0)
; #define PG8_LDB(dst, b, h) do { _Pragma("unroll") for (int n = 0; n < 2; ++n) _Pragma("unroll") for (int k = 0; k < 2; ++k) dst[n][k] = *(const PG8_LAS bf16x8*)(lds + PG8_SB(b, h) + boff + n * 2048 + k * 1024); } while (0)
; #define PG8_MMA(ai, bj, At, Bt) do { __builtin_amdgcn_s_setprio(1); _Pragma("unroll") for (int m = 0; m < 4; ++m) _Pragma("unroll") for (int n = 0; n < 2; ++n) _Pragma("unroll") for (int k = 0; k < 2; ++k) \
;         acc[ai][bj][m][n] = mma16<Epi::F16>(Bt[n][k], At[m][k], acc[ai][bj][m][n]); __builtin_amdgcn_s_setprio(0); } while (0)
; #define PG8_WAIT_V(n) asm volatile("s_waitcnt vmcnt(" #n ")" ::: "memory")
; #define PG8_WAIT_L(n) asm volatile("s_waitcnt lgkmcnt(" #n ")" ::: "memory")
; template <class Epi, class Sched, bool ALIGN_EPI = false, bool SP2 = false>
; __device__ __forceinline__ void gemm_phase(PG8_LAS unsigned char* lds, const Gemm g, const Sched& S, const Epi& E, const int wave_in) {
;     ...
;         for (int t = 0; t < nt; t += 2) {
;             const bool last = (t == nt - 2);
;             const char* a1 = cA + (size_t)(t + 1) * kstep;
;             const char* a2 = last ? nA : cA + (size_t)(t + 2) * kstep; const char* b2 = last ? nB : cB + (size_t)(t + 2) * kstep;
;             const char* a3 = a2 + kstep; const char* b3 = b2 + kstep;
;             if (last && has_next) S.a_ready(nxt);
;             if constexpr (SP2) {
;             PG8_LDB(B0, 0, 0); PG8_LDB(B1, 0, 1); PG8_SCHED; PG8_LDA(At, 0, 0); PG8_STAGE(PG8_SA(1, 1), a1 + hstep, voffA);
;             PG8_WAIT_V(8); PG8_WAIT_L(0); PG8_BAR; PG8_MMA(0, 0, At, B0); PG8_MMA(0, 1, At, B1); PG8_BAR; PG8_SCHED;
;             PG8_LDA(At, 0, 1); PG8_STAGE(PG8_SB(0, 0), b2, voffB); PG8_STAGE(PG8_SB(0, 1), b2 + hstep, voffB); PG8_STAGE(PG8_SA(0, 0), a2, voffA);
;             PG8_WAIT_V(8); PG8_WAIT_L(0); PG8_BAR; PG8_MMA(1, 0, At, B0); PG8_MMA(1, 1, At, B1); PG8_BAR; PG8_SCHED;
.LBB0_1035:
	v_add_u32_e32 v130, s28, v179
	v_add_u32_e32 v154, s72, v179
	ds_read_b128 v[114:117], v130
	ds_read_b128 v[118:121], v130 offset:1024
	ds_read_b128 v[122:125], v130 offset:2048
	ds_read_b128 v[130:133], v130 offset:3072
	ds_read_b128 v[138:141], v154
	ds_read_b128 v[142:145], v154 offset:1024
	ds_read_b128 v[146:149], v154 offset:2048
	ds_read_b128 v[154:157], v154 offset:3072
	s_add_u32 s14, s60, 0xfffc0080
	s_addc_u32 s15, s61, -1
	s_cmp_eq_u32 s13, 12
	s_cselect_b32 s63, s10, s15
	s_cselect_b32 s62, s11, s14
	s_cselect_b32 s37, s53, s12
	s_cselect_b32 s36, s55, s83
	v_lshl_add_u64 v[204:205], s[60:61], 0, v[168:169]
	s_add_i32 m0, s5, 0xc000
	ds_read_b128 v[172:175], v183
	ds_read_b128 v[184:187], v183 offset:1024
	ds_read_b128 v[188:191], v183 offset:2048
	ds_read_b128 v[192:195], v183 offset:3072
	ds_read_b128 v[196:199], v183 offset:4096
	ds_read_b128 v[200:203], v183 offset:5120
	ds_read_b128 v[210:213], v183 offset:6144
	ds_read_b128 v[214:217], v183 offset:7168
	global_load_lds_dwordx4 v[204:205], off
	v_lshl_add_u64 v[204:205], s[60:61], 0, v[170:171]
	s_add_i32 m0, s5, 0xe000
	s_nop 0
	global_load_lds_dwordx4 v[204:205], off
	s_waitcnt vmcnt(8)
	s_waitcnt lgkmcnt(0)
	s_barrier
	s_setprio 1
	s_waitcnt lgkmcnt(0)
	v_mfma_f32_16x16x32_f16 v[158:161], v[114:117], v[172:175], v[158:161]
	v_mfma_f32_16x16x32_f16 v[150:153], v[122:125], v[172:175], v[150:153]
	v_mfma_f32_16x16x32_f16 v[110:113], v[114:117], v[188:191], v[110:113]
	v_mfma_f32_16x16x32_f16 v[106:109], v[122:125], v[188:191], v[106:109]
	v_mfma_f32_16x16x32_f16 v[94:97], v[114:117], v[196:199], v[94:97]
	v_mfma_f32_16x16x32_f16 v[90:93], v[122:125], v[196:199], v[90:93]
	v_mfma_f32_16x16x32_f16 v[78:81], v[114:117], v[210:213], v[78:81]
	v_mfma_f32_16x16x32_f16 v[74:77], v[122:125], v[210:213], v[74:77]
	v_mfma_f32_16x16x32_f16 v[158:161], v[118:121], v[184:187], v[158:161]
	v_mfma_f32_16x16x32_f16 v[150:153], v[130:133], v[184:187], v[150:153]
	v_mfma_f32_16x16x32_f16 v[110:113], v[118:121], v[192:195], v[110:113]
	v_mfma_f32_16x16x32_f16 v[106:109], v[130:133], v[192:195], v[106:109]
	v_mfma_f32_16x16x32_f16 v[94:97], v[118:121], v[200:203], v[94:97]
	v_mfma_f32_16x16x32_f16 v[90:93], v[130:133], v[200:203], v[90:93]
	v_mfma_f32_16x16x32_f16 v[78:81], v[118:121], v[214:217], v[78:81]
	v_mfma_f32_16x16x32_f16 v[74:77], v[130:133], v[214:217], v[74:77]
	s_setprio 0
	s_setprio 1
	v_mfma_f32_16x16x32_f16 v[134:137], v[138:141], v[172:175], v[134:137]
	v_mfma_f32_16x16x32_f16 v[126:129], v[146:149], v[172:175], v[126:129]
	v_mfma_f32_16x16x32_f16 v[102:105], v[138:141], v[188:191], v[102:105]
	v_mfma_f32_16x16x32_f16 v[98:101], v[146:149], v[188:191], v[98:101]
	v_mfma_f32_16x16x32_f16 v[86:89], v[138:141], v[196:199], v[86:89]
	v_mfma_f32_16x16x32_f16 v[82:85], v[146:149], v[196:199], v[82:85]
	v_mfma_f32_16x16x32_f16 v[70:73], v[138:141], v[210:213], v[70:73]
	v_mfma_f32_16x16x32_f16 v[66:69], v[146:149], v[210:213], v[66:69]
	v_mfma_f32_16x16x32_f16 v[134:137], v[142:145], v[184:187], v[134:137]
	v_mfma_f32_16x16x32_f16 v[126:129], v[154:157], v[184:187], v[126:129]
	v_mfma_f32_16x16x32_f16 v[102:105], v[142:145], v[192:195], v[102:105]
	v_mfma_f32_16x16x32_f16 v[98:101], v[154:157], v[192:195], v[98:101]
	v_mfma_f32_16x16x32_f16 v[86:89], v[142:145], v[200:203], v[86:89]
	v_mfma_f32_16x16x32_f16 v[82:85], v[154:157], v[200:203], v[82:85]
	v_mfma_f32_16x16x32_f16 v[70:73], v[142:145], v[214:217], v[70:73]
	v_mfma_f32_16x16x32_f16 v[66:69], v[154:157], v[214:217], v[66:69]
	s_setprio 0
	s_barrier
	s_add_i32 s14, s28, s4
	v_lshl_add_u64 v[204:205], s[36:37], 0, v[0:1]
	s_mov_b32 m0, s14
	ds_read_b128 v[172:175], v183 offset:16384
	ds_read_b128 v[184:187], v183 offset:17408
	ds_read_b128 v[188:191], v183 offset:18432
	ds_read_b128 v[192:195], v183 offset:19456
	ds_read_b128 v[196:199], v183 offset:20480
	ds_read_b128 v[200:203], v183 offset:21504
	ds_read_b128 v[210:213], v183 offset:22528
	ds_read_b128 v[214:217], v183 offset:23552
	global_load_lds_dwordx4 v[204:205], off
	s_add_i32 m0, s14, 0x2000
	s_add_u32 s14, s36, 0x40000
	v_lshl_add_u64 v[218:219], s[36:37], 0, v[166:167]
	s_addc_u32 s15, s37, 0
	s_add_i32 s16, s72, s4
	global_load_lds_dwordx4 v[218:219], off
	v_lshl_add_u64 v[220:221], s[14:15], 0, v[0:1]
	s_mov_b32 m0, s16
	v_lshl_add_u64 v[222:223], s[62:63], 0, v[164:165]
	global_load_lds_dwordx4 v[220:221], off
	v_lshl_add_u64 v[220:221], s[14:15], 0, v[166:167]
	s_add_i32 m0, s16, 0x2000
	s_nop 0
	global_load_lds_dwordx4 v[220:221], off
	v_lshl_add_u64 v[220:221], s[62:63], 0, v[162:163]
	s_mov_b32 m0, s5
	s_nop 0
	global_load_lds_dwordx4 v[220:221], off
	s_mov_b32 m0, s6
	s_nop 0
	global_load_lds_dwordx4 v[222:223], off
	s_waitcnt vmcnt(8)
	s_waitcnt lgkmcnt(0)
	s_barrier
; #define PG8_STAGE(bufoff, gbase, voff) do { _Pragma("unroll") for (int _i = 0; _i < 2; ++_i) \
;         __builtin_amdgcn_global_load_lds((const unsigned*)((const char*)(gbase) + (voff)[_i]), (PG8_LAS unsigned*)(lds + (bufoff) + ldsw + _i * 8192), 16, 0, 0); } while (0)
; #define PG8_LDA(dst, b, h) do { _Pragma("unroll") for (int m = 0; m < 4; ++m) _Pragma("unroll") for (int k = 0; k < 2; ++k) dst[m][k] = *(const PG8_LAS bf16x8*)(lds + PG8_SA(b, h) + aoff + m * 2048 + k * 1024); } while (0)
; #define PG8_LDB(dst, b, h) do { _Pragma("unroll") for (int n = 0; n < 2; ++n) _Pragma("unroll") for (int k = 0; k < 2; ++k) dst[n][k] = *(const PG8_LAS bf16x8*)(lds + PG8_SB(b, h) + boff + n * 2048 + k * 1024); } while (0)
; #define PG8_MMA(ai, bj, At, Bt) do { __builtin_amdgcn_s_setprio(1); _Pragma("unroll") for (int m = 0; m < 4; ++m) _Pragma("unroll") for (int n = 0; n < 2; ++n) _Pragma("unroll") for (int k = 0; k < 2; ++k) \
;         acc[ai][bj][m][n] = mma16<Epi::F16>(Bt[n][k], At[m][k], acc[ai][bj][m][n]); __builtin_amdgcn_s_setprio(0); } while (0)
; #define PG8_WAIT_V(n) asm volatile("s_waitcnt vmcnt(" #n ")" ::: "memory")
; #define PG8_WAIT_L(n) asm volatile("s_waitcnt lgkmcnt(" #n ")" ::: "memory")
; #define PG8_BAR __builtin_amdgcn_s_barrier()
; #define PG8_SCHED __builtin_amdgcn_sched_barrier(0)
; template <class Epi, class Sched, bool ALIGN_EPI = false, bool SP2 = false>
; __device__ __forceinline__ void gemm_phase(PG8_LAS unsigned char* lds, const Gemm g, const Sched& S, const Epi& E, const int wave_in) {
;     ...
;             PG8_WAIT_V(8); PG8_WAIT_L(0); PG8_BAR; PG8_MMA(1, 0, At, B0); PG8_MMA(1, 1, At, B1); PG8_BAR; PG8_SCHED;
;             PG8_LDB(B0, 1, 0); PG8_LDB(B1, 1, 1); PG8_SCHED; PG8_LDA(At, 1, 0); PG8_STAGE(PG8_SA(0, 1), a2 + hstep, voffA);
;             PG8_WAIT_V(8); PG8_WAIT_L(0); PG8_BAR; PG8_MMA(0, 0, At, B0); PG8_MMA(0, 1, At, B1); PG8_BAR; PG8_SCHED;
	s_setprio 1
	s_waitcnt lgkmcnt(0)
	v_mfma_f32_16x16x32_f16 v[62:65], v[114:117], v[172:175], v[62:65]
	v_mfma_f32_16x16x32_f16 v[58:61], v[122:125], v[172:175], v[58:61]
	v_mfma_f32_16x16x32_f16 v[46:49], v[114:117], v[188:191], v[46:49]
	v_mfma_f32_16x16x32_f16 v[42:45], v[122:125], v[188:191], v[42:45]
	v_mfma_f32_16x16x32_f16 v[30:33], v[114:117], v[196:199], v[30:33]
	v_mfma_f32_16x16x32_f16 v[26:29], v[122:125], v[196:199], v[26:29]
	v_mfma_f32_16x16x32_f16 v[14:17], v[114:117], v[210:213], v[14:17]
	v_mfma_f32_16x16x32_f16 v[10:13], v[122:125], v[210:213], v[10:13]
	v_mfma_f32_16x16x32_f16 v[62:65], v[118:121], v[184:187], v[62:65]
	v_mfma_f32_16x16x32_f16 v[58:61], v[130:133], v[184:187], v[58:61]
	v_mfma_f32_16x16x32_f16 v[46:49], v[118:121], v[192:195], v[46:49]
	v_mfma_f32_16x16x32_f16 v[42:45], v[130:133], v[192:195], v[42:45]
	v_mfma_f32_16x16x32_f16 v[30:33], v[118:121], v[200:203], v[30:33]
	v_mfma_f32_16x16x32_f16 v[26:29], v[130:133], v[200:203], v[26:29]
	v_mfma_f32_16x16x32_f16 v[14:17], v[118:121], v[214:217], v[14:17]
	v_mfma_f32_16x16x32_f16 v[10:13], v[130:133], v[214:217], v[10:13]
	s_setprio 0
	s_setprio 1
	v_mfma_f32_16x16x32_f16 v[54:57], v[138:141], v[172:175], v[54:57]
	v_mfma_f32_16x16x32_f16 v[50:53], v[146:149], v[172:175], v[50:53]
	v_mfma_f32_16x16x32_f16 v[38:41], v[138:141], v[188:191], v[38:41]
	v_mfma_f32_16x16x32_f16 v[34:37], v[146:149], v[188:191], v[34:37]
	v_mfma_f32_16x16x32_f16 v[22:25], v[138:141], v[196:199], v[22:25]
	v_mfma_f32_16x16x32_f16 v[18:21], v[146:149], v[196:199], v[18:21]
	v_mfma_f32_16x16x32_f16 v[6:9], v[138:141], v[210:213], v[6:9]
	v_mfma_f32_16x16x32_f16 v[2:5], v[146:149], v[210:213], v[2:5]
	v_mfma_f32_16x16x32_f16 v[54:57], v[142:145], v[184:187], v[54:57]
	v_mfma_f32_16x16x32_f16 v[50:53], v[154:157], v[184:187], v[50:53]
	v_mfma_f32_16x16x32_f16 v[38:41], v[142:145], v[192:195], v[38:41]
	v_mfma_f32_16x16x32_f16 v[34:37], v[154:157], v[192:195], v[34:37]
	v_mfma_f32_16x16x32_f16 v[22:25], v[142:145], v[200:203], v[22:25]
	v_mfma_f32_16x16x32_f16 v[18:21], v[154:157], v[200:203], v[18:21]
	v_mfma_f32_16x16x32_f16 v[6:9], v[142:145], v[214:217], v[6:9]
	v_mfma_f32_16x16x32_f16 v[2:5], v[154:157], v[214:217], v[2:5]
	s_setprio 0
	s_barrier
	v_add_u32_e32 v130, s73, v179
	v_add_u32_e32 v154, s74, v179
	ds_read_b128 v[114:117], v130
	ds_read_b128 v[118:121], v130 offset:1024
	ds_read_b128 v[122:125], v130 offset:2048
	ds_read_b128 v[130:133], v130 offset:3072
	ds_read_b128 v[138:141], v154
	ds_read_b128 v[142:145], v154 offset:1024
	ds_read_b128 v[146:149], v154 offset:2048
	ds_read_b128 v[154:157], v154 offset:3072
	s_add_u32 s14, s62, 0x40000
	s_addc_u32 s15, s63, 0
	s_mov_b32 m0, s7
	v_lshl_add_u64 v[224:225], s[14:15], 0, v[162:163]
	ds_read_b128 v[172:175], v183 offset:32768
	ds_read_b128 v[184:187], v183 offset:33792
	ds_read_b128 v[188:191], v183 offset:34816
	ds_read_b128 v[192:195], v183 offset:35840
	ds_read_b128 v[196:199], v183 offset:36864
	ds_read_b128 v[200:203], v183 offset:37888
	ds_read_b128 v[210:213], v183 offset:38912
	ds_read_b128 v[214:217], v183 offset:39936
	global_load_lds_dwordx4 v[224:225], off
	v_lshl_add_u64 v[224:225], s[14:15], 0, v[164:165]
	s_mov_b32 m0, s8
	s_nop 0
	global_load_lds_dwordx4 v[224:225], off
	s_waitcnt vmcnt(8)
	s_waitcnt lgkmcnt(0)
	s_barrier
	s_setprio 1
	s_waitcnt lgkmcnt(0)
	v_mfma_f32_16x16x32_f16 v[158:161], v[114:117], v[172:175], v[158:161]
	v_mfma_f32_16x16x32_f16 v[150:153], v[122:125], v[172:175], v[150:153]
	v_mfma_f32_16x16x32_f16 v[110:113], v[114:117], v[188:191], v[110:113]
	v_mfma_f32_16x16x32_f16 v[106:109], v[122:125], v[188:191], v[106:109]
	v_mfma_f32_16x16x32_f16 v[94:97], v[114:117], v[196:199], v[94:97]
	v_mfma_f32_16x16x32_f16 v[90:93], v[122:125], v[196:199], v[90:93]
	v_mfma_f32_16x16x32_f16 v[78:81], v[114:117], v[210:213], v[78:81]
	v_mfma_f32_16x16x32_f16 v[74:77], v[122:125], v[210:213], v[74:77]
	v_mfma_f32_16x16x32_f16 v[158:161], v[118:121], v[184:187], v[158:161]
	v_mfma_f32_16x16x32_f16 v[150:153], v[130:133], v[184:187], v[150:153]
	v_mfma_f32_16x16x32_f16 v[110:113], v[118:121], v[192:195], v[110:113]
	v_mfma_f32_16x16x32_f16 v[106:109], v[130:133], v[192:195], v[106:109]
	v_mfma_f32_16x16x32_f16 v[94:97], v[118:121], v[200:203], v[94:97]
	v_mfma_f32_16x16x32_f16 v[90:93], v[130:133], v[200:203], v[90:93]
	v_mfma_f32_16x16x32_f16 v[78:81], v[118:121], v[214:217], v[78:81]
	v_mfma_f32_16x16x32_f16 v[74:77], v[130:133], v[214:217], v[74:77]
	s_setprio 0
	s_setprio 1
	v_mfma_f32_16x16x32_f16 v[134:137], v[138:141], v[172:175], v[134:137]
	v_mfma_f32_16x16x32_f16 v[126:129], v[146:149], v[172:175], v[126:129]
	v_mfma_f32_16x16x32_f16 v[102:105], v[138:141], v[188:191], v[102:105]
	v_mfma_f32_16x16x32_f16 v[98:101], v[146:149], v[188:191], v[98:101]
	v_mfma_f32_16x16x32_f16 v[86:89], v[138:141], v[196:199], v[86:89]
	v_mfma_f32_16x16x32_f16 v[82:85], v[146:149], v[196:199], v[82:85]
	v_mfma_f32_16x16x32_f16 v[70:73], v[138:141], v[210:213], v[70:73]
	v_mfma_f32_16x16x32_f16 v[66:69], v[146:149], v[210:213], v[66:69]
	v_mfma_f32_16x16x32_f16 v[134:137], v[142:145], v[184:187], v[134:137]
	v_mfma_f32_16x16x32_f16 v[126:129], v[154:157], v[184:187], v[126:129]
	v_mfma_f32_16x16x32_f16 v[102:105], v[142:145], v[192:195], v[102:105]
	v_mfma_f32_16x16x32_f16 v[98:101], v[154:157], v[192:195], v[98:101]
	v_mfma_f32_16x16x32_f16 v[86:89], v[142:145], v[200:203], v[86:89]
	v_mfma_f32_16x16x32_f16 v[82:85], v[154:157], v[200:203], v[82:85]
	v_mfma_f32_16x16x32_f16 v[70:73], v[142:145], v[214:217], v[70:73]
	v_mfma_f32_16x16x32_f16 v[66:69], v[154:157], v[214:217], v[66:69]
	s_setprio 0
	s_barrier
; #define PG8_STAGE(bufoff, gbase, voff) do { _Pragma("unroll") for (int _i = 0; _i < 2; ++_i) \
;         __builtin_amdgcn_global_load_lds((const unsigned*)((const char*)(gbase) + (voff)[_i]), (PG8_LAS unsigned*)(lds + (bufoff) + ldsw + _i * 8192), 16, 0, 0); } while (0)
; #define PG8_LDA(dst, b, h) do { _Pragma("unroll") for (int m = 0; m < 4; ++m) _Pragma("unroll") for (int k = 0; k < 2; ++k) dst[m][k] = *(const PG8_LAS bf16x8*)(lds + PG8_SA(b, h) + aoff + m * 2048 + k * 1024); } while (0)
; #define PG8_MMA(ai, bj, At, Bt) do { __builtin_amdgcn_s_setprio(1); _Pragma("unroll") for (int m = 0; m < 4; ++m) _Pragma("unroll") for (int n = 0; n < 2; ++n) _Pragma("unroll") for (int k = 0; k < 2; ++k) \
;         acc[ai][bj][m][n] = mma16<Epi::F16>(Bt[n][k], At[m][k], acc[ai][bj][m][n]); __builtin_amdgcn_s_setprio(0); } while (0)
; #define PG8_WAIT_V(n) asm volatile("s_waitcnt vmcnt(" #n ")" ::: "memory")
; #define PG8_WAIT_L(n) asm volatile("s_waitcnt lgkmcnt(" #n ")" ::: "memory")
; #define PG8_BAR __builtin_amdgcn_s_barrier()
; #define PG8_SCHED __builtin_amdgcn_sched_barrier(0)
; template <class Epi, class Sched, bool ALIGN_EPI = false, bool SP2 = false>
; __device__ __forceinline__ void gemm_phase(PG8_LAS unsigned char* lds, const Gemm g, const Sched& S, const Epi& E, const int wave_in) {
;     ...
;         for (int t = 0; t < nt; t += 2) {
;             const bool last = (t == nt - 2);
;             const char* a1 = cA + (size_t)(t + 1) * kstep;
;             const char* a2 = last ? nA : cA + (size_t)(t + 2) * kstep; const char* b2 = last ? nB : cB + (size_t)(t + 2) * kstep;
;             const char* a3 = a2 + kstep; const char* b3 = b2 + kstep;
;             if (last && has_next) S.a_ready(nxt);
;     ...
;             PG8_LDA(At, 1, 1); PG8_STAGE(PG8_SB(1, 0), b3, voffB); PG8_STAGE(PG8_SB(1, 1), b3 + hstep, voffB); PG8_STAGE(PG8_SA(1, 0), a3, voffA);
;             PG8_WAIT_V(8); PG8_WAIT_L(0); PG8_BAR; PG8_MMA(1, 0, At, B0); PG8_MMA(1, 1, At, B1); PG8_BAR; PG8_SCHED;
	s_add_i32 s14, s73, s4
	v_lshl_add_u64 v[204:205], v[204:205], 0, s[78:79]
	s_mov_b32 m0, s14
	ds_read_b128 v[172:175], v183 offset:49152
	ds_read_b128 v[184:187], v183 offset:50176
	ds_read_b128 v[188:191], v183 offset:51200
	ds_read_b128 v[192:195], v183 offset:52224
	ds_read_b128 v[196:199], v183 offset:53248
	ds_read_b128 v[200:203], v183 offset:54272
	ds_read_b128 v[210:213], v183 offset:55296
	ds_read_b128 v[214:217], v183 offset:56320
	global_load_lds_dwordx4 v[204:205], off
	s_add_i32 m0, s14, 0x2000
	s_add_u32 s14, s36, 0x40080
	v_lshl_add_u64 v[204:205], v[218:219], 0, s[78:79]
	s_addc_u32 s15, s37, 0
	s_add_i32 s16, s74, s4
	global_load_lds_dwordx4 v[204:205], off
	v_lshl_add_u64 v[204:205], s[14:15], 0, v[0:1]
	s_mov_b32 m0, s16
	s_nop 0
	global_load_lds_dwordx4 v[204:205], off
	v_lshl_add_u64 v[204:205], s[14:15], 0, v[166:167]
	s_add_i32 m0, s16, 0x2000
	s_nop 0
	global_load_lds_dwordx4 v[204:205], off
	v_lshl_add_u64 v[204:205], v[220:221], 0, s[78:79]
	s_mov_b32 m0, s9
	s_nop 0
	global_load_lds_dwordx4 v[204:205], off
	v_lshl_add_u64 v[204:205], v[222:223], 0, s[78:79]
	s_mov_b32 m0, s49
	s_nop 0
	global_load_lds_dwordx4 v[204:205], off
	s_waitcnt vmcnt(8)
	s_waitcnt lgkmcnt(0)
	s_barrier
	s_setprio 1
	s_waitcnt lgkmcnt(0)
	v_mfma_f32_16x16x32_f16 v[62:65], v[114:117], v[172:175], v[62:65]
	v_mfma_f32_16x16x32_f16 v[58:61], v[122:125], v[172:175], v[58:61]
	v_mfma_f32_16x16x32_f16 v[46:49], v[114:117], v[188:191], v[46:49]
	v_mfma_f32_16x16x32_f16 v[42:45], v[122:125], v[188:191], v[42:45]
	v_mfma_f32_16x16x32_f16 v[30:33], v[114:117], v[196:199], v[30:33]
	v_mfma_f32_16x16x32_f16 v[26:29], v[122:125], v[196:199], v[26:29]
	v_mfma_f32_16x16x32_f16 v[14:17], v[114:117], v[210:213], v[14:17]
	v_mfma_f32_16x16x32_f16 v[10:13], v[122:125], v[210:213], v[10:13]
	v_mfma_f32_16x16x32_f16 v[62:65], v[118:121], v[184:187], v[62:65]
	v_mfma_f32_16x16x32_f16 v[58:61], v[130:133], v[184:187], v[58:61]
	v_mfma_f32_16x16x32_f16 v[46:49], v[118:121], v[192:195], v[46:49]
	v_mfma_f32_16x16x32_f16 v[42:45], v[130:133], v[192:195], v[42:45]
	v_mfma_f32_16x16x32_f16 v[30:33], v[118:121], v[200:203], v[30:33]
	v_mfma_f32_16x16x32_f16 v[26:29], v[130:133], v[200:203], v[26:29]
	v_mfma_f32_16x16x32_f16 v[14:17], v[118:121], v[214:217], v[14:17]
	v_mfma_f32_16x16x32_f16 v[10:13], v[130:133], v[214:217], v[10:13]
	s_setprio 0
	s_setprio 1
	v_mfma_f32_16x16x32_f16 v[54:57], v[138:141], v[172:175], v[54:57]
	v_mfma_f32_16x16x32_f16 v[50:53], v[146:149], v[172:175], v[50:53]
	v_mfma_f32_16x16x32_f16 v[38:41], v[138:141], v[188:191], v[38:41]
	v_mfma_f32_16x16x32_f16 v[34:37], v[146:149], v[188:191], v[34:37]
	v_mfma_f32_16x16x32_f16 v[22:25], v[138:141], v[196:199], v[22:25]
	v_mfma_f32_16x16x32_f16 v[18:21], v[146:149], v[196:199], v[18:21]
	v_mfma_f32_16x16x32_f16 v[6:9], v[138:141], v[210:213], v[6:9]
	v_mfma_f32_16x16x32_f16 v[2:5], v[146:149], v[210:213], v[2:5]
	v_mfma_f32_16x16x32_f16 v[54:57], v[142:145], v[184:187], v[54:57]
	v_mfma_f32_16x16x32_f16 v[50:53], v[154:157], v[184:187], v[50:53]
	v_mfma_f32_16x16x32_f16 v[38:41], v[142:145], v[192:195], v[38:41]
	v_mfma_f32_16x16x32_f16 v[34:37], v[154:157], v[192:195], v[34:37]
	v_mfma_f32_16x16x32_f16 v[22:25], v[142:145], v[200:203], v[22:25]
	v_mfma_f32_16x16x32_f16 v[18:21], v[154:157], v[200:203], v[18:21]
	v_mfma_f32_16x16x32_f16 v[6:9], v[142:145], v[214:217], v[6:9]
	v_mfma_f32_16x16x32_f16 v[2:5], v[154:157], v[214:217], v[2:5]
	s_setprio 0
	s_add_i32 s13, s13, 2
	s_add_u32 s60, s60, 0x100
	s_addc_u32 s61, s61, 0
	s_add_u32 s83, s83, 0x100
	s_addc_u32 s12, s12, 0
	s_cmp_gt_u32 s13, 13
	s_barrier
	s_cbranch_scc0 .LBB0_1035
	s_and_b64 vcc, exec, s[50:51]
	s_cbranch_vccz .LBB0_1038
	s_barrier

; #define PG8_STAGE(bufoff, gbase, voff) do { _Pragma("unroll") for (int _i = 0; _i < 2; ++_i) \
;         __builtin_amdgcn_global_load_lds((const unsigned*)((const char*)(gbase) + (voff)[_i]), (PG8_LAS unsigned*)(lds + (bufoff) + ldsw + _i * 8192), 16, 0, 0); } while (0)
; #define PG8_LDA(dst, b, h) do { _Pragma("unroll") for (int m = 0; m < 4; ++m) _Pragma("unroll") for (int k = 0; k < 2; ++k) dst[m][k] = *(const PG8_LAS bf16x8*)(lds + PG8_SA(b, h) + aoff + m * 2048 + k * 1024); } while (0)
; #define PG8_LDB(dst, b, h) do { _Pragma("unroll") for (int n = 0; n < 2; ++n) _Pragma("unroll") for (int k = 0; k < 2; ++k) dst[n][k] = *(const PG8_LAS bf16x8*)(lds + PG8_SB(b, h) + boff + n * 2048 + k * 1024); } while (0)
; #define PG8_MMA(ai, bj, At, Bt) do { __builtin_amdgcn_s_setprio(1); _Pragma("unroll") for (int m = 0; m < 4; ++m) _Pragma("unroll") for (int n = 0; n < 2; ++n) _Pragma("unroll") for (int k = 0; k < 2; ++k) \
;         acc[ai][bj][m][n] = mma16<Epi::F16>(Bt[n][k], At[m][k], acc[ai][bj][m][n]); __builtin_amdgcn_s_setprio(0); } while (0)
; #define PG8_WAIT_V(n) asm volatile("s_waitcnt vmcnt(" #n ")" ::: "memory")
; #define PG8_WAIT_L(n) asm volatile("s_waitcnt lgkmcnt(" #n ")" ::: "memory")
; template <class Epi, class Sched, bool ALIGN_EPI = false, bool SP2 = false>
; __device__ __forceinline__ void gemm_phase(PG8_LAS unsigned char* lds, const Gemm g, const Sched& S, const Epi& E, const int wave_in) {
;     ...
;         for (int t = 0; t < nt; t += 2) {
;             const bool last = (t == nt - 2);
;             const char* a1 = cA + (size_t)(t + 1) * kstep;
;             const char* a2 = last ? nA : cA + (size_t)(t + 2) * kstep; const char* b2 = last ? nB : cB + (size_t)(t + 2) * kstep;
;             const char* a3 = a2 + kstep; const char* b3 = b2 + kstep;
;             if (last && has_next) S.a_ready(nxt);
;             if constexpr (SP2) {
;             PG8_LDB(B0, 0, 0); PG8_LDB(B1, 0, 1); PG8_SCHED; PG8_LDA(At, 0, 0); PG8_STAGE(PG8_SA(1, 1), a1 + hstep, voffA);
;             PG8_WAIT_V(8); PG8_WAIT_L(0); PG8_BAR; PG8_MMA(0, 0, At, B0); PG8_MMA(0, 1, At, B1); PG8_BAR; PG8_SCHED;
;             PG8_LDA(At, 0, 1); PG8_STAGE(PG8_SB(0, 0), b2, voffB); PG8_STAGE(PG8_SB(0, 1), b2 + hstep, voffB); PG8_STAGE(PG8_SA(0, 0), a2, voffA);
;             PG8_WAIT_V(8); PG8_WAIT_L(0); PG8_BAR; PG8_MMA(1, 0, At, B0); PG8_MMA(1, 1, At, B1); PG8_BAR; PG8_SCHED;
.LBB0_1133:
	v_add_u32_e32 v58, s28, v211
	v_add_u32_e32 v78, s72, v211
	ds_read_b128 v[42:45], v58
	ds_read_b128 v[46:49], v58 offset:1024
	ds_read_b128 v[54:57], v58 offset:2048
	ds_read_b128 v[58:61], v58 offset:3072
	ds_read_b128 v[66:69], v78
	ds_read_b128 v[70:73], v78 offset:1024
	ds_read_b128 v[74:77], v78 offset:2048
	ds_read_b128 v[78:81], v78 offset:3072
	s_add_u32 s60, s58, 0x100
	s_addc_u32 s61, s59, 0
	s_cmp_eq_u32 s13, 40
	s_cselect_b32 s63, s45, s61
	s_cselect_b32 s62, s44, s60
	s_cselect_b32 s37, s57, s12
	s_cselect_b32 s36, s56, s11
	v_lshl_add_u64 v[178:179], s[58:59], 0, v[220:221]
	s_add_i32 m0, s1, 0xc000
	ds_read_b128 v[98:101], v213
	ds_read_b128 v[102:105], v213 offset:1024
	ds_read_b128 v[106:109], v213 offset:2048
	ds_read_b128 v[118:121], v213 offset:3072
	ds_read_b128 v[130:133], v213 offset:4096
	ds_read_b128 v[138:141], v213 offset:5120
	ds_read_b128 v[146:149], v213 offset:6144
	ds_read_b128 v[158:161], v213 offset:7168
	global_load_lds_dwordx4 v[178:179], off
	v_lshl_add_u64 v[178:179], s[58:59], 0, v[222:223]
	s_add_i32 m0, s1, 0xe000
	s_nop 0
	global_load_lds_dwordx4 v[178:179], off
	s_waitcnt vmcnt(8)
	s_waitcnt lgkmcnt(0)
	s_barrier
	s_setprio 1
	s_waitcnt lgkmcnt(0)
	v_mfma_f32_16x16x32_bf16 v[190:193], v[54:57], v[98:101], v[190:193]
	v_mfma_f32_16x16x32_bf16 v[174:177], v[42:45], v[106:109], v[174:177]
	v_mfma_f32_16x16x32_bf16 v[170:173], v[54:57], v[106:109], v[170:173]
	v_mfma_f32_16x16x32_bf16 v[154:157], v[42:45], v[130:133], v[154:157]
	v_mfma_f32_16x16x32_bf16 v[150:153], v[54:57], v[130:133], v[150:153]
	v_mfma_f32_16x16x32_bf16 v[126:129], v[42:45], v[146:149], v[126:129]
	v_mfma_f32_16x16x32_bf16 v[122:125], v[54:57], v[146:149], v[122:125]
	v_mfma_f32_16x16x32_bf16 v[178:181], v[42:45], v[98:101], v[194:197]
	v_mfma_f32_16x16x32_bf16 v[190:193], v[58:61], v[102:105], v[190:193]
	v_mfma_f32_16x16x32_bf16 v[174:177], v[46:49], v[118:121], v[174:177]
	v_mfma_f32_16x16x32_bf16 v[170:173], v[58:61], v[118:121], v[170:173]
	v_mfma_f32_16x16x32_bf16 v[154:157], v[46:49], v[138:141], v[154:157]
	v_mfma_f32_16x16x32_bf16 v[150:153], v[58:61], v[138:141], v[150:153]
	v_mfma_f32_16x16x32_bf16 v[126:129], v[46:49], v[158:161], v[126:129]
	v_mfma_f32_16x16x32_bf16 v[122:125], v[58:61], v[158:161], v[122:125]
	v_mfma_f32_16x16x32_bf16 v[178:181], v[46:49], v[102:105], v[178:181]
	s_setprio 0
	s_setprio 1
	v_mfma_f32_16x16x32_bf16 v[186:189], v[66:69], v[98:101], v[186:189]
	v_mfma_f32_16x16x32_bf16 v[98:101], v[74:77], v[98:101], v[182:185]
	v_mfma_f32_16x16x32_bf16 v[186:189], v[70:73], v[102:105], v[186:189]
	v_mfma_f32_16x16x32_bf16 v[98:101], v[78:81], v[102:105], v[98:101]
	v_mfma_f32_16x16x32_bf16 v[102:105], v[66:69], v[106:109], v[166:169]
	v_mfma_f32_16x16x32_bf16 v[106:109], v[74:77], v[106:109], v[162:165]
	v_mfma_f32_16x16x32_bf16 v[114:117], v[66:69], v[146:149], v[114:117]
	v_mfma_f32_16x16x32_bf16 v[110:113], v[74:77], v[146:149], v[110:113]
	v_mfma_f32_16x16x32_bf16 v[102:105], v[70:73], v[118:121], v[102:105]
	v_mfma_f32_16x16x32_bf16 v[106:109], v[78:81], v[118:121], v[106:109]
	v_mfma_f32_16x16x32_bf16 v[118:121], v[66:69], v[130:133], v[142:145]
	v_mfma_f32_16x16x32_bf16 v[130:133], v[74:77], v[130:133], v[134:137]
	v_mfma_f32_16x16x32_bf16 v[114:117], v[70:73], v[158:161], v[114:117]
	v_mfma_f32_16x16x32_bf16 v[110:113], v[78:81], v[158:161], v[110:113]
	v_mfma_f32_16x16x32_bf16 v[118:121], v[70:73], v[138:141], v[118:121]
	v_mfma_f32_16x16x32_bf16 v[130:133], v[78:81], v[138:141], v[130:133]
	s_setprio 0
	s_barrier
	s_add_i32 s14, s28, s0
	v_lshl_add_u64 v[228:229], s[36:37], 0, v[0:1]
	s_mov_b32 m0, s14
	ds_read_b128 v[134:137], v213 offset:16384
	ds_read_b128 v[138:141], v213 offset:17408
	ds_read_b128 v[142:145], v213 offset:18432
	ds_read_b128 v[146:149], v213 offset:19456
	ds_read_b128 v[158:161], v213 offset:20480
	ds_read_b128 v[162:165], v213 offset:21504
	ds_read_b128 v[166:169], v213 offset:22528
	ds_read_b128 v[182:185], v213 offset:23552
	global_load_lds_dwordx4 v[228:229], off
	s_add_i32 m0, s14, 0x2000
	s_add_u32 s14, s36, 0xb0000
	v_lshl_add_u64 v[230:231], s[36:37], 0, v[218:219]
	s_addc_u32 s15, s37, 0
	s_add_i32 s16, s72, s0
	global_load_lds_dwordx4 v[230:231], off
	v_lshl_add_u64 v[194:195], s[14:15], 0, v[0:1]
	s_mov_b32 m0, s16
	v_lshl_add_u64 v[232:233], s[62:63], 0, v[214:215]
	global_load_lds_dwordx4 v[194:195], off
	v_lshl_add_u64 v[194:195], s[14:15], 0, v[218:219]
	s_add_i32 m0, s16, 0x2000
	v_lshl_add_u64 v[234:235], s[62:63], 0, v[216:217]
	global_load_lds_dwordx4 v[194:195], off
	s_mov_b32 m0, s1
	s_nop 0
	global_load_lds_dwordx4 v[232:233], off
	s_mov_b32 m0, s4
	s_nop 0
	global_load_lds_dwordx4 v[234:235], off
	s_waitcnt vmcnt(8)
	s_waitcnt lgkmcnt(0)
	s_barrier
; #define PG8_STAGE(bufoff, gbase, voff) do { _Pragma("unroll") for (int _i = 0; _i < 2; ++_i) \
;         __builtin_amdgcn_global_load_lds((const unsigned*)((const char*)(gbase) + (voff)[_i]), (PG8_LAS unsigned*)(lds + (bufoff) + ldsw + _i * 8192), 16, 0, 0); } while (0)
; #define PG8_LDA(dst, b, h) do { _Pragma("unroll") for (int m = 0; m < 4; ++m) _Pragma("unroll") for (int k = 0; k < 2; ++k) dst[m][k] = *(const PG8_LAS bf16x8*)(lds + PG8_SA(b, h) + aoff + m * 2048 + k * 1024); } while (0)
; #define PG8_LDB(dst, b, h) do { _Pragma("unroll") for (int n = 0; n < 2; ++n) _Pragma("unroll") for (int k = 0; k < 2; ++k) dst[n][k] = *(const PG8_LAS bf16x8*)(lds + PG8_SB(b, h) + boff + n * 2048 + k * 1024); } while (0)
; #define PG8_MMA(ai, bj, At, Bt) do { __builtin_amdgcn_s_setprio(1); _Pragma("unroll") for (int m = 0; m < 4; ++m) _Pragma("unroll") for (int n = 0; n < 2; ++n) _Pragma("unroll") for (int k = 0; k < 2; ++k) \
;         acc[ai][bj][m][n] = mma16<Epi::F16>(Bt[n][k], At[m][k], acc[ai][bj][m][n]); __builtin_amdgcn_s_setprio(0); } while (0)
; #define PG8_WAIT_V(n) asm volatile("s_waitcnt vmcnt(" #n ")" ::: "memory")
; #define PG8_WAIT_L(n) asm volatile("s_waitcnt lgkmcnt(" #n ")" ::: "memory")
; #define PG8_BAR __builtin_amdgcn_s_barrier()
; #define PG8_SCHED __builtin_amdgcn_sched_barrier(0)
; template <class Epi, class Sched, bool ALIGN_EPI = false, bool SP2 = false>
; __device__ __forceinline__ void gemm_phase(PG8_LAS unsigned char* lds, const Gemm g, const Sched& S, const Epi& E, const int wave_in) {
;     ...
;             PG8_WAIT_V(8); PG8_WAIT_L(0); PG8_BAR; PG8_MMA(1, 0, At, B0); PG8_MMA(1, 1, At, B1); PG8_BAR; PG8_SCHED;
;             PG8_LDB(B0, 1, 0); PG8_LDB(B1, 1, 1); PG8_SCHED; PG8_LDA(At, 1, 0); PG8_STAGE(PG8_SA(0, 1), a2 + hstep, voffA);
;             PG8_WAIT_V(8); PG8_WAIT_L(0); PG8_BAR; PG8_MMA(0, 0, At, B0); PG8_MMA(0, 1, At, B1); PG8_BAR; PG8_SCHED;
	s_setprio 1
	s_waitcnt lgkmcnt(0)
	v_mfma_f32_16x16x32_bf16 v[94:97], v[42:45], v[134:137], v[94:97]
	v_mfma_f32_16x16x32_bf16 v[90:93], v[54:57], v[134:137], v[90:93]
	v_mfma_f32_16x16x32_bf16 v[62:65], v[42:45], v[142:145], v[62:65]
	v_mfma_f32_16x16x32_bf16 v[50:53], v[54:57], v[142:145], v[50:53]
	v_mfma_f32_16x16x32_bf16 v[30:33], v[42:45], v[158:161], v[30:33]
	v_mfma_f32_16x16x32_bf16 v[26:29], v[54:57], v[158:161], v[26:29]
	v_mfma_f32_16x16x32_bf16 v[14:17], v[42:45], v[166:169], v[14:17]
	v_mfma_f32_16x16x32_bf16 v[10:13], v[54:57], v[166:169], v[10:13]
	v_mfma_f32_16x16x32_bf16 v[94:97], v[46:49], v[138:141], v[94:97]
	v_mfma_f32_16x16x32_bf16 v[90:93], v[58:61], v[138:141], v[90:93]
	v_mfma_f32_16x16x32_bf16 v[62:65], v[46:49], v[146:149], v[62:65]
	v_mfma_f32_16x16x32_bf16 v[50:53], v[58:61], v[146:149], v[50:53]
	v_mfma_f32_16x16x32_bf16 v[30:33], v[46:49], v[162:165], v[30:33]
	v_mfma_f32_16x16x32_bf16 v[26:29], v[58:61], v[162:165], v[26:29]
	v_mfma_f32_16x16x32_bf16 v[14:17], v[46:49], v[182:185], v[14:17]
	v_mfma_f32_16x16x32_bf16 v[10:13], v[58:61], v[182:185], v[10:13]
	s_setprio 0
	s_setprio 1
	v_mfma_f32_16x16x32_bf16 v[38:41], v[66:69], v[142:145], v[38:41]
	v_mfma_f32_16x16x32_bf16 v[34:37], v[74:77], v[142:145], v[34:37]
	v_mfma_f32_16x16x32_bf16 v[22:25], v[66:69], v[158:161], v[22:25]
	v_mfma_f32_16x16x32_bf16 v[18:21], v[74:77], v[158:161], v[18:21]
	v_mfma_f32_16x16x32_bf16 v[6:9], v[66:69], v[166:169], v[6:9]
	v_mfma_f32_16x16x32_bf16 v[2:5], v[74:77], v[166:169], v[2:5]
	v_mfma_f32_16x16x32_bf16 v[42:45], v[66:69], v[134:137], v[86:89]
	v_mfma_f32_16x16x32_bf16 v[46:49], v[74:77], v[134:137], v[82:85]
	v_mfma_f32_16x16x32_bf16 v[38:41], v[70:73], v[146:149], v[38:41]
	v_mfma_f32_16x16x32_bf16 v[34:37], v[78:81], v[146:149], v[34:37]
	v_mfma_f32_16x16x32_bf16 v[22:25], v[70:73], v[162:165], v[22:25]
	v_mfma_f32_16x16x32_bf16 v[18:21], v[78:81], v[162:165], v[18:21]
	v_mfma_f32_16x16x32_bf16 v[6:9], v[70:73], v[182:185], v[6:9]
	v_mfma_f32_16x16x32_bf16 v[2:5], v[78:81], v[182:185], v[2:5]
	v_mfma_f32_16x16x32_bf16 v[42:45], v[70:73], v[138:141], v[42:45]
	v_mfma_f32_16x16x32_bf16 v[46:49], v[78:81], v[138:141], v[46:49]
	s_setprio 0
	s_barrier
	v_add_u32_e32 v70, s73, v211
	v_add_u32_e32 v82, s74, v211
	ds_read_b128 v[54:57], v70
	ds_read_b128 v[58:61], v70 offset:1024
	ds_read_b128 v[66:69], v70 offset:2048
	ds_read_b128 v[70:73], v70 offset:3072
	ds_read_b128 v[74:77], v82
	ds_read_b128 v[78:81], v82 offset:1024
	ds_read_b128 v[138:141], v82 offset:2048
	ds_read_b128 v[146:149], v82 offset:3072
	s_add_u32 s14, s62, 0xb0000
	s_addc_u32 s15, s63, 0
	s_mov_b32 m0, s5
	v_lshl_add_u64 v[162:163], s[14:15], 0, v[214:215]
	ds_read_b128 v[82:85], v213 offset:32768
	ds_read_b128 v[86:89], v213 offset:33792
	ds_read_b128 v[134:137], v213 offset:34816
	ds_read_b128 v[142:145], v213 offset:35840
	ds_read_b128 v[158:161], v213 offset:36864
	ds_read_b128 v[198:201], v213 offset:37888
	ds_read_b128 v[202:205], v213 offset:38912
	ds_read_b128 v[224:227], v213 offset:39936
	global_load_lds_dwordx4 v[162:163], off
	v_lshl_add_u64 v[162:163], s[14:15], 0, v[216:217]
	s_mov_b32 m0, s71
	s_nop 0
	global_load_lds_dwordx4 v[162:163], off
	s_waitcnt vmcnt(8)
	s_waitcnt lgkmcnt(0)
	s_barrier
	s_setprio 1
	s_waitcnt lgkmcnt(0)
	v_mfma_f32_16x16x32_bf16 v[162:165], v[54:57], v[82:85], v[178:181]
	v_mfma_f32_16x16x32_bf16 v[194:197], v[58:61], v[86:89], v[162:165]
	v_mfma_f32_16x16x32_bf16 v[162:165], v[66:69], v[82:85], v[190:193]
	v_mfma_f32_16x16x32_bf16 v[190:193], v[70:73], v[86:89], v[162:165]
	v_mfma_f32_16x16x32_bf16 v[162:165], v[54:57], v[134:137], v[174:177]
	v_mfma_f32_16x16x32_bf16 v[174:177], v[58:61], v[142:145], v[162:165]
	v_mfma_f32_16x16x32_bf16 v[162:165], v[66:69], v[134:137], v[170:173]
	v_mfma_f32_16x16x32_bf16 v[154:157], v[54:57], v[158:161], v[154:157]
	v_mfma_f32_16x16x32_bf16 v[150:153], v[66:69], v[158:161], v[150:153]
	v_mfma_f32_16x16x32_bf16 v[126:129], v[54:57], v[202:205], v[126:129]
	v_mfma_f32_16x16x32_bf16 v[122:125], v[66:69], v[202:205], v[122:125]
	v_mfma_f32_16x16x32_bf16 v[170:173], v[70:73], v[142:145], v[162:165]
	v_mfma_f32_16x16x32_bf16 v[154:157], v[58:61], v[198:201], v[154:157]
	v_mfma_f32_16x16x32_bf16 v[150:153], v[70:73], v[198:201], v[150:153]
	v_mfma_f32_16x16x32_bf16 v[126:129], v[58:61], v[224:227], v[126:129]
	v_mfma_f32_16x16x32_bf16 v[122:125], v[70:73], v[224:227], v[122:125]
	s_setprio 0
	s_setprio 1
	v_mfma_f32_16x16x32_bf16 v[162:165], v[74:77], v[82:85], v[186:189]
	v_mfma_f32_16x16x32_bf16 v[82:85], v[138:141], v[82:85], v[98:101]
	v_mfma_f32_16x16x32_bf16 v[182:185], v[146:149], v[86:89], v[82:85]
	v_mfma_f32_16x16x32_bf16 v[82:85], v[74:77], v[134:137], v[102:105]
	v_mfma_f32_16x16x32_bf16 v[166:169], v[78:81], v[142:145], v[82:85]
	v_mfma_f32_16x16x32_bf16 v[82:85], v[138:141], v[134:137], v[106:109]
	v_mfma_f32_16x16x32_bf16 v[186:189], v[78:81], v[86:89], v[162:165]
	v_mfma_f32_16x16x32_bf16 v[162:165], v[146:149], v[142:145], v[82:85]
	v_mfma_f32_16x16x32_bf16 v[82:85], v[74:77], v[158:161], v[118:121]
	v_mfma_f32_16x16x32_bf16 v[142:145], v[78:81], v[198:201], v[82:85]
	v_mfma_f32_16x16x32_bf16 v[82:85], v[138:141], v[158:161], v[130:133]
	v_mfma_f32_16x16x32_bf16 v[134:137], v[146:149], v[198:201], v[82:85]
	v_mfma_f32_16x16x32_bf16 v[82:85], v[74:77], v[202:205], v[114:117]
	v_mfma_f32_16x16x32_bf16 v[114:117], v[78:81], v[224:227], v[82:85]
	v_mfma_f32_16x16x32_bf16 v[82:85], v[138:141], v[202:205], v[110:113]
	v_mfma_f32_16x16x32_bf16 v[110:113], v[146:149], v[224:227], v[82:85]
	s_setprio 0
	s_barrier
; #define PG8_STAGE(bufoff, gbase, voff) do { _Pragma("unroll") for (int _i = 0; _i < 2; ++_i) \
;         __builtin_amdgcn_global_load_lds((const unsigned*)((const char*)(gbase) + (voff)[_i]), (PG8_LAS unsigned*)(lds + (bufoff) + ldsw + _i * 8192), 16, 0, 0); } while (0)
; #define PG8_LDA(dst, b, h) do { _Pragma("unroll") for (int m = 0; m < 4; ++m) _Pragma("unroll") for (int k = 0; k < 2; ++k) dst[m][k] = *(const PG8_LAS bf16x8*)(lds + PG8_SA(b, h) + aoff + m * 2048 + k * 1024); } while (0)
; #define PG8_MMA(ai, bj, At, Bt) do { __builtin_amdgcn_s_setprio(1); _Pragma("unroll") for (int m = 0; m < 4; ++m) _Pragma("unroll") for (int n = 0; n < 2; ++n) _Pragma("unroll") for (int k = 0; k < 2; ++k) \
;         acc[ai][bj][m][n] = mma16<Epi::F16>(Bt[n][k], At[m][k], acc[ai][bj][m][n]); __builtin_amdgcn_s_setprio(0); } while (0)
; #define PG8_WAIT_V(n) asm volatile("s_waitcnt vmcnt(" #n ")" ::: "memory")
; #define PG8_WAIT_L(n) asm volatile("s_waitcnt lgkmcnt(" #n ")" ::: "memory")
; #define PG8_BAR __builtin_amdgcn_s_barrier()
; #define PG8_SCHED __builtin_amdgcn_sched_barrier(0)
; template <class Epi, class Sched, bool ALIGN_EPI = false, bool SP2 = false>
; __device__ __forceinline__ void gemm_phase(PG8_LAS unsigned char* lds, const Gemm g, const Sched& S, const Epi& E, const int wave_in) {
;     ...
;         for (int t = 0; t < nt; t += 2) {
;             const bool last = (t == nt - 2);
;             const char* a1 = cA + (size_t)(t + 1) * kstep;
;             const char* a2 = last ? nA : cA + (size_t)(t + 2) * kstep; const char* b2 = last ? nB : cB + (size_t)(t + 2) * kstep;
;             const char* a3 = a2 + kstep; const char* b3 = b2 + kstep;
;             if (last && has_next) S.a_ready(nxt);
;     ...
;             PG8_LDA(At, 1, 1); PG8_STAGE(PG8_SB(1, 0), b3, voffB); PG8_STAGE(PG8_SB(1, 1), b3 + hstep, voffB); PG8_STAGE(PG8_SA(1, 0), a3, voffA);
;             PG8_WAIT_V(8); PG8_WAIT_L(0); PG8_BAR; PG8_MMA(1, 0, At, B0); PG8_MMA(1, 1, At, B1); PG8_BAR; PG8_SCHED;
	s_add_i32 s14, s73, s0
	v_lshl_add_u64 v[86:87], v[228:229], 0, s[78:79]
	s_mov_b32 m0, s14
	s_nop 1
	ds_read_b128 v[82:85], v213 offset:49152
	ds_read_b128 v[98:101], v213 offset:50176
	ds_read_b128 v[102:105], v213 offset:51200
	ds_read_b128 v[106:109], v213 offset:52224
	ds_read_b128 v[118:121], v213 offset:53248
	ds_read_b128 v[130:133], v213 offset:54272
	ds_read_b128 v[158:161], v213 offset:55296
	ds_read_b128 v[178:181], v213 offset:56320
	global_load_lds_dwordx4 v[86:87], off
	s_add_i32 m0, s14, 0x2000
	s_add_u32 s14, s36, 0xb0080
	v_lshl_add_u64 v[86:87], v[230:231], 0, s[78:79]
	s_addc_u32 s15, s37, 0
	s_add_i32 s16, s74, s0
	global_load_lds_dwordx4 v[86:87], off
	v_lshl_add_u64 v[86:87], s[14:15], 0, v[0:1]
	s_mov_b32 m0, s16
	s_nop 0
	global_load_lds_dwordx4 v[86:87], off
	v_lshl_add_u64 v[86:87], s[14:15], 0, v[218:219]
	s_add_i32 m0, s16, 0x2000
	s_nop 0
	global_load_lds_dwordx4 v[86:87], off
	v_lshl_add_u64 v[86:87], v[232:233], 0, s[78:79]
	s_mov_b32 m0, s6
	s_nop 0
	global_load_lds_dwordx4 v[86:87], off
	v_lshl_add_u64 v[86:87], v[234:235], 0, s[78:79]
	s_mov_b32 m0, s7
	s_nop 0
	global_load_lds_dwordx4 v[86:87], off
	s_waitcnt vmcnt(8)
	s_waitcnt lgkmcnt(0)
	s_barrier
	s_setprio 1
	s_waitcnt lgkmcnt(0)
	v_mfma_f32_16x16x32_bf16 v[86:89], v[54:57], v[82:85], v[94:97]
	v_mfma_f32_16x16x32_bf16 v[94:97], v[58:61], v[98:101], v[86:89]
	v_mfma_f32_16x16x32_bf16 v[86:89], v[66:69], v[82:85], v[90:93]
	v_mfma_f32_16x16x32_bf16 v[62:65], v[54:57], v[102:105], v[62:65]
	v_mfma_f32_16x16x32_bf16 v[50:53], v[66:69], v[102:105], v[50:53]
	v_mfma_f32_16x16x32_bf16 v[30:33], v[54:57], v[118:121], v[30:33]
	v_mfma_f32_16x16x32_bf16 v[26:29], v[66:69], v[118:121], v[26:29]
	v_mfma_f32_16x16x32_bf16 v[14:17], v[54:57], v[158:161], v[14:17]
	v_mfma_f32_16x16x32_bf16 v[10:13], v[66:69], v[158:161], v[10:13]
	v_mfma_f32_16x16x32_bf16 v[90:93], v[70:73], v[98:101], v[86:89]
	v_mfma_f32_16x16x32_bf16 v[62:65], v[58:61], v[106:109], v[62:65]
	v_mfma_f32_16x16x32_bf16 v[50:53], v[70:73], v[106:109], v[50:53]
	v_mfma_f32_16x16x32_bf16 v[30:33], v[58:61], v[130:133], v[30:33]
	v_mfma_f32_16x16x32_bf16 v[26:29], v[70:73], v[130:133], v[26:29]
	v_mfma_f32_16x16x32_bf16 v[14:17], v[58:61], v[178:181], v[14:17]
	v_mfma_f32_16x16x32_bf16 v[10:13], v[70:73], v[178:181], v[10:13]
	s_setprio 0
	s_setprio 1
	v_mfma_f32_16x16x32_bf16 v[42:45], v[74:77], v[82:85], v[42:45]
	v_mfma_f32_16x16x32_bf16 v[86:89], v[78:81], v[98:101], v[42:45]
	v_mfma_f32_16x16x32_bf16 v[42:45], v[138:141], v[82:85], v[46:49]
	v_mfma_f32_16x16x32_bf16 v[38:41], v[74:77], v[102:105], v[38:41]
	v_mfma_f32_16x16x32_bf16 v[34:37], v[138:141], v[102:105], v[34:37]
	v_mfma_f32_16x16x32_bf16 v[22:25], v[74:77], v[118:121], v[22:25]
	v_mfma_f32_16x16x32_bf16 v[18:21], v[138:141], v[118:121], v[18:21]
	v_mfma_f32_16x16x32_bf16 v[6:9], v[74:77], v[158:161], v[6:9]
	v_mfma_f32_16x16x32_bf16 v[2:5], v[138:141], v[158:161], v[2:5]
	v_mfma_f32_16x16x32_bf16 v[82:85], v[146:149], v[98:101], v[42:45]
	v_mfma_f32_16x16x32_bf16 v[38:41], v[78:81], v[106:109], v[38:41]
	v_mfma_f32_16x16x32_bf16 v[34:37], v[146:149], v[106:109], v[34:37]
	v_mfma_f32_16x16x32_bf16 v[22:25], v[78:81], v[130:133], v[22:25]
	v_mfma_f32_16x16x32_bf16 v[18:21], v[146:149], v[130:133], v[18:21]
	v_mfma_f32_16x16x32_bf16 v[6:9], v[78:81], v[178:181], v[6:9]
	v_mfma_f32_16x16x32_bf16 v[2:5], v[146:149], v[178:181], v[2:5]
	s_setprio 0
	s_add_i32 s13, s13, 2
	s_add_u32 s11, s11, 0x100
	s_addc_u32 s12, s12, 0
	s_cmp_gt_u32 s13, 41
	s_mov_b64 s[58:59], s[60:61]
	s_barrier
	s_cbranch_scc0 .LBB0_1133
	s_and_b64 vcc, exec, s[54:55]
	s_cbranch_vccz .LBB0_1136
	s_barrier
